# lever 4 in the RG-LRU phase: s_setprio 1 for the two scan waves while they run the serial scan (conv waves share their SIMDs)
# speedup vs baseline: 1.0013x; 1.0013x over previous
; #define LAS __attribute__((address_space(3)))
; __device__ __forceinline__ float bf1(bf16_t h) { return __uint_as_float(((unsigned)h) << 16); }
; __device__ __forceinline__ float fast_sigmoid(float x) { return __builtin_amdgcn_rcpf(1.0f + __builtin_amdgcn_exp2f(-1.44269504089f * x)); }
; __device__ __forceinline__ void lru_item(const Args& a, int l, int item, LAS unsigned char* lds) {
;     ...
;         {
;             f32x4 accA[4], accX[4]; bf16x8 af[4][4]; bf16_t xr[4][4];
; #pragma unroll
;             for (int rb = 0; rb < 4; ++rb)
; #pragma unroll
;                 for (int ks = 0; ks < 4; ++ks) af[rb][ks] = *(const LAS bf16x8*)(At + (16 * rb + fr) * LRU_AS + (32 * ks + 8 * fq) * 2);
; #pragma unroll
;             for (int rb = 0; rb < 4; ++rb)
; #pragma unroll
;                 for (int j = 0; j < 4; ++j) xr[rb][j] = *(const LAS bf16_t*)(At + (16 * rb + 4 * fq + j) * LRU_AS + ecol * 2);
;             __builtin_amdgcn_sched_barrier(0);
; #pragma unroll
;             for (int rb = 0; rb < 4; ++rb) { accA[rb] = (f32x4){0.f, 0.f, 0.f, 0.f}; accX[rb] = (f32x4){0.f, 0.f, 0.f, 0.f}; }
; #pragma unroll
;             for (int ks = 0; ks < 4; ++ks)
; #pragma unroll
;                 for (int rb = 0; rb < 4; ++rb) {
;                     accA[rb] = __builtin_amdgcn_mfma_f32_16x16x32_bf16(af[rb][ks], wfa[ks], accA[rb], 0, 0, 0);
;                     accX[rb] = __builtin_amdgcn_mfma_f32_16x16x32_bf16(af[rb][ks], wfx[ks], accX[rb], 0, 0, 0);
;                 }
; #pragma unroll
;             for (int rb = 0; rb < 4; ++rb)
; #pragma unroll
;                 for (int j = 0; j < 4; ++j) {
;                     const int tt = 16 * rb + 4 * fq + j;
;                     const float xcv = bf1(xr[rb][j]);
;                     const float r = fast_sigmoid(accA[rb][j] + e_ba), ig = fast_sigmoid(accX[rb][j] + e_bx);
;                     const float la = e_coef * r;
;                     const float av = __builtin_amdgcn_exp2f(1.44269504089f * la);
;                     const float om = 1.0f - __builtin_amdgcn_exp2f(2.88539008178f * la);
;                     const float bv = __builtin_amdgcn_sqrtf(fmaxf(om, 0.f)) * ig * xcv;
;                     LA[tt * LRU_FS + ecol] = av; LB[tt * LRU_FS + ecol] = bv;
;                 }
.LBB0_209:
	ds_read_b128 v[88:91], v161
	ds_read_b128 v[92:95], v161 offset:64
	ds_read_b128 v[168:171], v161 offset:128
	ds_read_b128 v[172:175], v161 offset:192
	ds_read_b128 v[176:179], v161 offset:4352
	ds_read_b128 v[180:183], v161 offset:4416
	ds_read_b128 v[184:187], v161 offset:4480
	ds_read_b128 v[188:191], v161 offset:4544
	ds_read_b128 v[192:195], v161 offset:8704
	ds_read_b128 v[210:213], v161 offset:8768
	ds_read_b128 v[214:217], v161 offset:8832
	ds_read_b128 v[218:221], v161 offset:8896
	ds_read_b128 v[222:225], v161 offset:13056
	ds_read_b128 v[226:229], v161 offset:13120
	ds_read_b128 v[230:233], v161 offset:13184
	ds_read_b128 v[234:237], v161 offset:13248
	ds_read_u16 v3, v162
	ds_read_u16 v167, v163
	ds_read_u16 v196, v163 offset:272
	ds_read_u16 v197, v163 offset:544
	ds_read_u16 v209, v163 offset:4080
	ds_read_u16 v242, v163 offset:4352
	ds_read_u16 v243, v163 offset:4624
	ds_read_u16 v244, v163 offset:4896
	ds_read_u16 v245, v163 offset:8432
	ds_read_u16 v246, v163 offset:8704
	ds_read_u16 v247, v163 offset:8976
	ds_read_u16 v248, v163 offset:9248
	ds_read_u16 v249, v163 offset:12784
	ds_read_u16 v250, v163 offset:13056
	ds_read_u16 v2, v163 offset:13328
	ds_read_u16 v1, v163 offset:13600
	s_waitcnt lgkmcnt(14)
	v_mfma_f32_16x16x32_bf16 v[238:241], v[88:91], v[4:7], 0
	v_lshlrev_b32_e32 v3, 16, v3
	v_lshlrev_b32_e32 v167, 16, v167
	s_waitcnt lgkmcnt(1)
	v_lshlrev_b32_e32 v2, 16, v2
	v_mfma_f32_16x16x32_bf16 v[88:91], v[88:91], v[8:11], 0
	s_waitcnt lgkmcnt(0)
	v_lshlrev_b32_e32 v1, 16, v1
	v_mfma_f32_16x16x32_bf16 v[238:241], v[92:95], v[12:15], v[238:241]
	v_mfma_f32_16x16x32_bf16 v[88:91], v[92:95], v[16:19], v[88:91]
	v_mfma_f32_16x16x32_bf16 v[92:95], v[168:171], v[20:23], v[238:241]
	v_mfma_f32_16x16x32_bf16 v[92:95], v[172:175], v[28:31], v[92:95]
	v_mfma_f32_16x16x32_bf16 v[88:91], v[168:171], v[24:27], v[88:91]
	v_mfma_f32_16x16x32_bf16 v[88:91], v[172:175], v[32:35], v[88:91]
	s_nop 5
	v_add_f32_e32 v92, v122, v92
	v_mul_f32_e32 v92, 0xbfb8aa3b, v92
	v_exp_f32_e32 v92, v92
	v_add_f32_e32 v93, v122, v93
	v_mul_f32_e32 v93, 0xbfb8aa3b, v93
	v_add_f32_e32 v88, v123, v88
	v_add_f32_e32 v92, 1.0, v92
	v_rcp_f32_e32 v92, v92
	v_mul_f32_e32 v88, 0xbfb8aa3b, v88
	v_exp_f32_e32 v88, v88
	v_exp_f32_e32 v93, v93
	v_mul_f32_e32 v92, v100, v92
	v_mul_f32_e32 v168, 0x4038aa3b, v92
	v_exp_f32_e32 v168, v168
	v_add_f32_e32 v88, 1.0, v88
	v_rcp_f32_e32 v88, v88
	v_add_f32_e32 v93, 1.0, v93
	v_sub_f32_e32 v168, 1.0, v168
	v_max_f32_e32 v172, 0, v168
	v_sqrt_f32_e32 v238, v172
	v_rcp_f32_e32 v93, v93
	v_mul_f32_e32 v92, 0x3fb8aa3b, v92
	v_exp_f32_e32 v92, v92
	v_mul_f32_e32 v88, v88, v238
	v_mul_f32_e32 v3, v88, v3
	ds_write_b32 v120, v3
	v_mul_f32_e32 v3, v100, v93
	v_mul_f32_e32 v88, 0x4038aa3b, v3
	v_mul_f32_e32 v3, 0x3fb8aa3b, v3
	v_exp_f32_e32 v3, v3
	ds_write_b32 v103, v92 offset:34816
	v_add_f32_e32 v89, v123, v89
	v_mul_f32_e32 v89, 0xbfb8aa3b, v89
	ds_write_b32 v121, v3 offset:34816
	v_add_f32_e32 v3, v122, v94
	v_mul_f32_e32 v3, 0xbfb8aa3b, v3
	v_exp_f32_e32 v88, v88
	v_exp_f32_e32 v3, v3
	v_exp_f32_e32 v89, v89
	v_mfma_f32_16x16x32_bf16 v[168:171], v[176:179], v[4:7], 0
	v_sub_f32_e32 v88, 1.0, v88
	v_add_f32_e32 v3, 1.0, v3
	v_add_f32_e32 v89, 1.0, v89
	v_max_f32_e32 v88, 0, v88
	v_rcp_f32_e32 v3, v3
	v_rcp_f32_e32 v89, v89
	v_sqrt_f32_e32 v88, v88
	v_mfma_f32_16x16x32_bf16 v[172:175], v[176:179], v[8:11], 0
	v_mul_f32_e32 v3, v100, v3
	v_mul_f32_e32 v88, v89, v88
	v_add_f32_e32 v89, v123, v90
	v_mul_f32_e32 v90, 0x4038aa3b, v3
	v_mul_f32_e32 v3, 0x3fb8aa3b, v3
	v_exp_f32_e32 v3, v3
	v_mul_f32_e32 v88, v88, v167
	ds_write_b32 v124, v88
	v_mul_f32_e32 v89, 0xbfb8aa3b, v89
	v_exp_f32_e32 v90, v90
	ds_write_b32 v125, v3 offset:34816
	v_add_f32_e32 v3, v122, v95
	v_exp_f32_e32 v89, v89
	v_mul_f32_e32 v3, 0xbfb8aa3b, v3
	v_exp_f32_e32 v3, v3
	v_sub_f32_e32 v90, 1.0, v90
	v_add_f32_e32 v89, 1.0, v89
	v_max_f32_e32 v90, 0, v90
	v_rcp_f32_e32 v89, v89
	v_sqrt_f32_e32 v90, v90
	v_add_f32_e32 v3, 1.0, v3
	v_rcp_f32_e32 v3, v3
	v_mfma_f32_16x16x32_bf16 v[168:171], v[180:183], v[12:15], v[168:171]
	v_lshlrev_b32_e32 v88, 16, v196
	v_mul_f32_e32 v89, v89, v90
	v_mul_f32_e32 v88, v89, v88
	v_mfma_f32_16x16x32_bf16 v[172:175], v[180:183], v[16:19], v[172:175]
	v_mul_f32_e32 v3, v100, v3
	ds_write_b32 v126, v88
	v_add_f32_e32 v88, v123, v91
	v_mfma_f32_16x16x32_bf16 v[176:179], v[192:195], v[4:7], 0
	v_lshlrev_b32_e32 v167, 16, v197
	v_mfma_f32_16x16x32_bf16 v[192:195], v[192:195], v[8:11], 0
	v_mfma_f32_16x16x32_bf16 v[168:171], v[184:187], v[20:23], v[168:171]
	v_mfma_f32_16x16x32_bf16 v[172:175], v[184:187], v[24:27], v[172:175]
	v_mul_f32_e32 v185, 0x4038aa3b, v3
	v_mul_f32_e32 v184, 0xbfb8aa3b, v88
	v_exp_f32_e32 v185, v185
	v_exp_f32_e32 v184, v184
	v_mfma_f32_16x16x32_bf16 v[180:183], v[210:213], v[16:19], v[192:195]
	v_mul_f32_e32 v3, 0x3fb8aa3b, v3
	v_sub_f32_e32 v185, 1.0, v185
	v_add_f32_e32 v184, 1.0, v184
	v_max_f32_e32 v185, 0, v185
	v_mfma_f32_16x16x32_bf16 v[92:95], v[214:217], v[24:27], v[180:183]
	v_rcp_f32_e32 v184, v184
	v_sqrt_f32_e32 v185, v185
	v_exp_f32_e32 v3, v3
	v_mfma_f32_16x16x32_bf16 v[168:171], v[188:191], v[28:31], v[168:171]
	ds_write_b32 v127, v3 offset:34816
	v_mfma_f32_16x16x32_bf16 v[172:175], v[188:191], v[32:35], v[172:175]
	v_mul_f32_e32 v188, v184, v185
	s_nop 4
	v_add_f32_e32 v169, v122, v169
	v_mul_f32_e32 v169, 0xbfb8aa3b, v169
	v_mfma_f32_16x16x32_bf16 v[184:187], v[218:221], v[32:35], v[92:95]
	v_exp_f32_e32 v169, v169
	v_mul_f32_e32 v167, v188, v167
	ds_write_b32 v128, v167
	v_add_f32_e32 v92, v122, v168
	v_mul_f32_e32 v92, 0xbfb8aa3b, v92
	v_exp_f32_e32 v168, v92
; __device__ __forceinline__ float bf1(bf16_t h) { return __uint_as_float(((unsigned)h) << 16); }
; __device__ __forceinline__ float fast_sigmoid(float x) { return __builtin_amdgcn_rcpf(1.0f + __builtin_amdgcn_exp2f(-1.44269504089f * x)); }
; __device__ __forceinline__ void lru_item(const Args& a, int l, int item, LAS unsigned char* lds) {
;     ...
; #pragma unroll
;             for (int rb = 0; rb < 4; ++rb)
; #pragma unroll
;                 for (int j = 0; j < 4; ++j) {
;                     const int tt = 16 * rb + 4 * fq + j;
;                     const float xcv = bf1(xr[rb][j]);
;                     const float r = fast_sigmoid(accA[rb][j] + e_ba), ig = fast_sigmoid(accX[rb][j] + e_bx);
;                     const float la = e_coef * r;
;                     const float av = __builtin_amdgcn_exp2f(1.44269504089f * la);
;                     const float om = 1.0f - __builtin_amdgcn_exp2f(2.88539008178f * la);
;                     const float bv = __builtin_amdgcn_sqrtf(fmaxf(om, 0.f)) * ig * xcv;
;                     LA[tt * LRU_FS + ecol] = av; LB[tt * LRU_FS + ecol] = bv;
;                 }
	v_lshlrev_b32_e32 v167, 16, v209
	v_add_f32_e32 v170, v122, v170
	v_mul_f32_e32 v170, 0xbfb8aa3b, v170
	v_add_f32_e32 v3, 1.0, v168
	v_rcp_f32_e32 v3, v3
	v_add_f32_e32 v168, v123, v172
	v_mul_f32_e32 v168, 0xbfb8aa3b, v168
	v_exp_f32_e32 v168, v168
	v_mul_f32_e32 v3, v100, v3
	v_mul_f32_e32 v172, 0x4038aa3b, v3
	v_exp_f32_e32 v172, v172
	v_mul_f32_e32 v3, 0x3fb8aa3b, v3
	v_exp_f32_e32 v3, v3
	v_add_f32_e32 v168, 1.0, v168
	v_sub_f32_e32 v172, 1.0, v172
	v_max_f32_e32 v172, 0, v172
	ds_write_b32 v129, v3 offset:34816
	v_add_f32_e32 v3, 1.0, v169
	v_rcp_f32_e32 v168, v168
	v_sqrt_f32_e32 v172, v172
	v_rcp_f32_e32 v3, v3
	v_exp_f32_e32 v170, v170
	v_mfma_f32_16x16x32_bf16 v[176:179], v[210:213], v[12:15], v[176:179]
	v_mul_f32_e32 v168, v168, v172
	v_mul_f32_e32 v3, v100, v3
	v_mul_f32_e32 v167, v168, v167
	v_add_f32_e32 v168, v123, v173
	v_mul_f32_e32 v169, 0x4038aa3b, v3
	v_mul_f32_e32 v168, 0xbfb8aa3b, v168
	v_exp_f32_e32 v169, v169
	v_mul_f32_e32 v3, 0x3fb8aa3b, v3
	v_exp_f32_e32 v168, v168
	v_exp_f32_e32 v3, v3
	v_sub_f32_e32 v169, 1.0, v169
	ds_write_b32 v130, v167
	v_add_f32_e32 v168, 1.0, v168
	v_max_f32_e32 v169, 0, v169
	ds_write_b32 v131, v3 offset:34816
	v_add_f32_e32 v3, 1.0, v170
	v_rcp_f32_e32 v168, v168
	v_sqrt_f32_e32 v169, v169
	v_rcp_f32_e32 v3, v3
	v_lshlrev_b32_e32 v167, 16, v242
	v_add_f32_e32 v170, v122, v171
	v_mul_f32_e32 v168, v168, v169
	v_mul_f32_e32 v3, v100, v3
	v_mul_f32_e32 v167, v168, v167
	v_add_f32_e32 v168, v123, v174
	v_mul_f32_e32 v169, 0x4038aa3b, v3
	v_mul_f32_e32 v168, 0xbfb8aa3b, v168
	v_exp_f32_e32 v169, v169
	v_mul_f32_e32 v3, 0x3fb8aa3b, v3
	v_mul_f32_e32 v170, 0xbfb8aa3b, v170
	v_exp_f32_e32 v168, v168
	v_exp_f32_e32 v3, v3
	v_exp_f32_e32 v170, v170
	v_mfma_f32_16x16x32_bf16 v[176:179], v[214:217], v[20:23], v[176:179]
	v_sub_f32_e32 v169, 1.0, v169
	ds_write_b32 v132, v167
	v_add_f32_e32 v168, 1.0, v168
	v_max_f32_e32 v169, 0, v169
	ds_write_b32 v133, v3 offset:34816
	v_add_f32_e32 v3, 1.0, v170
	v_rcp_f32_e32 v168, v168
	v_sqrt_f32_e32 v169, v169
	v_rcp_f32_e32 v3, v3
	v_mfma_f32_16x16x32_bf16 v[176:179], v[218:221], v[28:31], v[176:179]
	v_lshlrev_b32_e32 v167, 16, v243
	v_mul_f32_e32 v168, v168, v169
	v_mul_f32_e32 v3, v100, v3
	v_mul_f32_e32 v167, v168, v167
	v_add_f32_e32 v168, v123, v175
	v_mul_f32_e32 v169, 0x4038aa3b, v3
	s_nop 1
	v_add_f32_e32 v170, v122, v176
	v_mul_f32_e32 v168, 0xbfb8aa3b, v168
	v_exp_f32_e32 v169, v169
	v_mul_f32_e32 v3, 0x3fb8aa3b, v3
	v_mul_f32_e32 v170, 0xbfb8aa3b, v170
	v_exp_f32_e32 v168, v168
	v_exp_f32_e32 v3, v3
	v_exp_f32_e32 v170, v170
	v_sub_f32_e32 v169, 1.0, v169
	ds_write_b32 v134, v167
	v_add_f32_e32 v168, 1.0, v168
	v_max_f32_e32 v169, 0, v169
	ds_write_b32 v135, v3 offset:34816
	v_add_f32_e32 v3, 1.0, v170
	v_rcp_f32_e32 v168, v168
	v_sqrt_f32_e32 v169, v169
	v_rcp_f32_e32 v3, v3
	v_lshlrev_b32_e32 v167, 16, v244
	v_add_f32_e32 v170, v122, v177
	v_mul_f32_e32 v168, v168, v169
	v_mul_f32_e32 v3, v100, v3
	v_mul_f32_e32 v167, v168, v167
	v_add_f32_e32 v168, v123, v184
	v_mul_f32_e32 v169, 0x4038aa3b, v3
	v_mul_f32_e32 v168, 0xbfb8aa3b, v168
	v_exp_f32_e32 v169, v169
	v_mul_f32_e32 v3, 0x3fb8aa3b, v3
	v_mul_f32_e32 v170, 0xbfb8aa3b, v170
	v_exp_f32_e32 v168, v168
	v_exp_f32_e32 v3, v3
	v_exp_f32_e32 v170, v170
	v_sub_f32_e32 v169, 1.0, v169
	ds_write_b32 v136, v167
	v_add_f32_e32 v168, 1.0, v168
	v_max_f32_e32 v169, 0, v169
	ds_write_b32 v137, v3 offset:34816
	v_add_f32_e32 v3, 1.0, v170
	v_rcp_f32_e32 v168, v168
	v_sqrt_f32_e32 v169, v169
	v_rcp_f32_e32 v3, v3
	v_lshlrev_b32_e32 v167, 16, v245
	v_add_f32_e32 v170, v122, v178
	v_mul_f32_e32 v168, v168, v169
	v_mul_f32_e32 v3, v100, v3
	v_mul_f32_e32 v167, v168, v167
	v_add_f32_e32 v168, v123, v185
	v_mul_f32_e32 v169, 0x4038aa3b, v3
	v_mul_f32_e32 v168, 0xbfb8aa3b, v168
	v_exp_f32_e32 v169, v169
	v_mul_f32_e32 v3, 0x3fb8aa3b, v3
	v_mul_f32_e32 v170, 0xbfb8aa3b, v170
	v_exp_f32_e32 v168, v168
	v_exp_f32_e32 v3, v3
	v_exp_f32_e32 v170, v170
	v_sub_f32_e32 v169, 1.0, v169
	ds_write_b32 v138, v167
	v_add_f32_e32 v168, 1.0, v168
	v_max_f32_e32 v169, 0, v169
	ds_write_b32 v139, v3 offset:34816
	v_add_f32_e32 v3, 1.0, v170
	v_rcp_f32_e32 v168, v168
	v_sqrt_f32_e32 v169, v169
	v_rcp_f32_e32 v3, v3
	v_mfma_f32_16x16x32_bf16 v[238:241], v[222:225], v[4:7], 0
	v_lshlrev_b32_e32 v167, 16, v246
	v_mul_f32_e32 v168, v168, v169
	v_mul_f32_e32 v3, v100, v3
	v_mul_f32_e32 v167, v168, v167
	v_add_f32_e32 v168, v123, v186
	v_mul_f32_e32 v169, 0x4038aa3b, v3
	v_add_f32_e32 v170, v122, v179
	v_mfma_f32_16x16x32_bf16 v[192:195], v[226:229], v[12:15], v[238:241]
	v_mul_f32_e32 v168, 0xbfb8aa3b, v168
	v_exp_f32_e32 v169, v169
	v_mul_f32_e32 v3, 0x3fb8aa3b, v3
	v_mul_f32_e32 v170, 0xbfb8aa3b, v170
	v_exp_f32_e32 v168, v168
	v_exp_f32_e32 v3, v3
	v_exp_f32_e32 v170, v170
	v_mfma_f32_16x16x32_bf16 v[180:183], v[230:233], v[20:23], v[192:195]
	v_sub_f32_e32 v169, 1.0, v169
	ds_write_b32 v140, v167
	v_add_f32_e32 v168, 1.0, v168
	v_max_f32_e32 v169, 0, v169
	ds_write_b32 v141, v3 offset:34816
	v_add_f32_e32 v3, 1.0, v170
	v_rcp_f32_e32 v168, v168
	v_sqrt_f32_e32 v169, v169
	v_rcp_f32_e32 v3, v3
	v_mfma_f32_16x16x32_bf16 v[222:225], v[222:225], v[8:11], 0
	v_lshlrev_b32_e32 v167, 16, v247
	v_mul_f32_e32 v168, v168, v169
	v_mul_f32_e32 v3, v100, v3
	v_mfma_f32_16x16x32_bf16 v[92:95], v[234:237], v[28:31], v[180:183]
	v_mul_f32_e32 v167, v168, v167
	v_add_f32_e32 v168, v123, v187
	v_mul_f32_e32 v169, 0x4038aa3b, v3
	v_mfma_f32_16x16x32_bf16 v[210:213], v[226:229], v[16:19], v[222:225]
	v_mul_f32_e32 v168, 0xbfb8aa3b, v168
	v_exp_f32_e32 v169, v169
	s_nop 1
	v_add_f32_e32 v92, v122, v92
	v_exp_f32_e32 v168, v168
; #define LAS __attribute__((address_space(3)))
; __device__ __forceinline__ unsigned cvt_pk_bf16(float lo, float hi) { unsigned r; asm volatile("v_cvt_pk_bf16_f32 %0, %1, %2" : "=v"(r) : "v"(lo), "v"(hi)); return r; }
; __device__ __forceinline__ float bf1(bf16_t h) { return __uint_as_float(((unsigned)h) << 16); }
; __device__ __forceinline__ float fast_sigmoid(float x) { return __builtin_amdgcn_rcpf(1.0f + __builtin_amdgcn_exp2f(-1.44269504089f * x)); }
; __device__ __forceinline__ void lds_barrier() { asm volatile("s_waitcnt lgkmcnt(0)" ::: "memory"); __builtin_amdgcn_s_barrier(); asm volatile("" ::: "memory"); }
; __device__ __forceinline__ void lru_item(const Args& a, int l, int item, LAS unsigned char* lds) {
;     ...
;             for (int rb = 0; rb < 4; ++rb)
; #pragma unroll
;                 for (int j = 0; j < 4; ++j) {
;                     const int tt = 16 * rb + 4 * fq + j;
;                     const float xcv = bf1(xr[rb][j]);
;                     const float r = fast_sigmoid(accA[rb][j] + e_ba), ig = fast_sigmoid(accX[rb][j] + e_bx);
;                     const float la = e_coef * r;
;                     const float av = __builtin_amdgcn_exp2f(1.44269504089f * la);
;                     const float om = 1.0f - __builtin_amdgcn_exp2f(2.88539008178f * la);
;                     const float bv = __builtin_amdgcn_sqrtf(fmaxf(om, 0.f)) * ig * xcv;
;                     LA[tt * LRU_FS + ecol] = av; LB[tt * LRU_FS + ecol] = bv;
;                 }
;         }
;         lds_barrier();
;         if (tid < 128) {
; #pragma unroll 1
;             for (int t0 = 0; t0 < 64; t0 += 16) {
;                 float av[16], bv[16];
; #pragma unroll
;                 for (int i = 0; i < 16; ++i) { av[i] = LA[(t0 + i) * LRU_FS + tid]; bv[i] = LB[(t0 + i) * LRU_FS + tid]; }
; #pragma unroll
;                 for (int i = 0; i < 16; ++i) { hstate = av[i] * hstate + bv[i]; av[i] = hstate; }
; #pragma unroll
;                 for (int i = 0; i < 16; ++i) *(LAS bf16_t*)(HO + (t0 + i) * LRU_AS + tid * 2) = (bf16_t)(cvt_pk_bf16(av[i], 0.f) & 0xffffu);
;             }
;         }
	v_mul_f32_e32 v3, 0x3fb8aa3b, v3
	v_mul_f32_e32 v92, 0xbfb8aa3b, v92
	v_exp_f32_e32 v3, v3
	v_exp_f32_e32 v92, v92
	v_mfma_f32_16x16x32_bf16 v[88:91], v[230:233], v[24:27], v[210:213]
	v_sub_f32_e32 v169, 1.0, v169
	v_add_f32_e32 v168, 1.0, v168
	v_max_f32_e32 v169, 0, v169
	ds_write_b32 v142, v167
	v_rcp_f32_e32 v168, v168
	v_sqrt_f32_e32 v169, v169
	ds_write_b32 v143, v3 offset:34816
	v_add_f32_e32 v3, 1.0, v92
	v_rcp_f32_e32 v3, v3
	v_mfma_f32_16x16x32_bf16 v[88:91], v[234:237], v[32:35], v[88:91]
	v_lshlrev_b32_e32 v167, 16, v248
	v_mul_f32_e32 v168, v168, v169
	v_mul_f32_e32 v167, v168, v167
	v_mul_f32_e32 v3, v100, v3
	ds_write_b32 v144, v167
	s_nop 2
	v_add_f32_e32 v88, v123, v88
	v_mul_f32_e32 v167, 0x4038aa3b, v3
	v_add_f32_e32 v93, v122, v93
	v_mul_f32_e32 v88, 0xbfb8aa3b, v88
	v_exp_f32_e32 v167, v167
	v_mul_f32_e32 v3, 0x3fb8aa3b, v3
	v_mul_f32_e32 v93, 0xbfb8aa3b, v93
	v_exp_f32_e32 v88, v88
	v_exp_f32_e32 v3, v3
	v_exp_f32_e32 v93, v93
	v_sub_f32_e32 v167, 1.0, v167
	v_add_f32_e32 v88, 1.0, v88
	v_max_f32_e32 v167, 0, v167
	ds_write_b32 v145, v3 offset:34816
	v_add_f32_e32 v3, 1.0, v93
	v_rcp_f32_e32 v88, v88
	v_sqrt_f32_e32 v167, v167
	v_rcp_f32_e32 v3, v3
	v_lshlrev_b32_e32 v92, 16, v249
	v_add_f32_e32 v89, v123, v89
	v_mul_f32_e32 v88, v88, v167
	v_mul_f32_e32 v3, v100, v3
	v_mul_f32_e32 v88, v88, v92
	v_mul_f32_e32 v92, 0x4038aa3b, v3
	v_mul_f32_e32 v89, 0xbfb8aa3b, v89
	v_exp_f32_e32 v92, v92
	v_exp_f32_e32 v89, v89
	v_add_f32_e32 v93, v122, v94
	v_mul_f32_e32 v3, 0x3fb8aa3b, v3
	v_sub_f32_e32 v92, 1.0, v92
	v_add_f32_e32 v89, 1.0, v89
	v_max_f32_e32 v92, 0, v92
	v_rcp_f32_e32 v89, v89
	v_sqrt_f32_e32 v92, v92
	v_mul_f32_e32 v93, 0xbfb8aa3b, v93
	v_exp_f32_e32 v3, v3
	v_exp_f32_e32 v93, v93
	ds_write_b32 v146, v88
	v_lshlrev_b32_e32 v88, 16, v250
	v_mul_f32_e32 v89, v89, v92
	v_mul_f32_e32 v88, v89, v88
	ds_write_b32 v147, v3 offset:34816
	v_add_f32_e32 v3, 1.0, v93
	v_add_f32_e32 v89, v123, v90
	v_mul_f32_e32 v89, 0xbfb8aa3b, v89
	v_rcp_f32_e32 v3, v3
	v_exp_f32_e32 v89, v89
	ds_write_b32 v148, v88
	v_add_f32_e32 v90, v122, v95
	v_mul_f32_e32 v3, v100, v3
	v_add_f32_e32 v88, 1.0, v89
	v_mul_f32_e32 v89, 0x4038aa3b, v3
	v_exp_f32_e32 v89, v89
	v_mul_f32_e32 v3, 0x3fb8aa3b, v3
	v_mul_f32_e32 v90, 0xbfb8aa3b, v90
	v_exp_f32_e32 v3, v3
	v_exp_f32_e32 v90, v90
	v_sub_f32_e32 v89, 1.0, v89
	v_max_f32_e32 v89, 0, v89
	v_rcp_f32_e32 v88, v88
	v_sqrt_f32_e32 v89, v89
	ds_write_b32 v149, v3 offset:34816
	v_add_f32_e32 v3, 1.0, v90
	v_rcp_f32_e32 v3, v3
	v_mul_f32_e32 v88, v88, v89
	v_mul_f32_e32 v2, v88, v2
	v_add_f32_e32 v88, v123, v91
	v_mul_f32_e32 v3, v100, v3
	v_mul_f32_e32 v88, 0xbfb8aa3b, v88
	v_mul_f32_e32 v89, 0x4038aa3b, v3
	v_exp_f32_e32 v88, v88
	v_exp_f32_e32 v89, v89
	ds_write_b32 v150, v2
	v_mul_f32_e32 v3, 0x3fb8aa3b, v3
	v_add_f32_e32 v2, 1.0, v88
	v_sub_f32_e32 v88, 1.0, v89
	v_max_f32_e32 v88, 0, v88
	v_rcp_f32_e32 v2, v2
	v_sqrt_f32_e32 v88, v88
	v_exp_f32_e32 v3, v3
	v_mul_f32_e32 v2, v2, v88
	v_mul_f32_e32 v1, v2, v1
	ds_write_b32 v151, v3 offset:34816
	ds_write_b32 v152, v1
	s_waitcnt lgkmcnt(0)
	s_barrier
	s_and_saveexec_b64 s[2:3], s[40:41]
	s_cbranch_execz .LBB0_213
	s_mov_b32 s1, -16
	v_mov_b32_e32 v1, v160
	v_mov_b32_e32 v2, v153
	s_setprio 1
.LBB0_211:
	v_add_u32_e32 v3, 0, v1
	v_add_u32_e32 v88, 0x8800, v3
	v_add_u32_e32 v90, 0x11800, v3
	v_add_u32_e32 v92, 0x11c80, v3
	v_add_u32_e32 v94, 0x12100, v3
	v_add_u32_e32 v168, 0x12580, v3
	v_add_u32_e32 v170, 0x12a00, v3
	v_add_u32_e32 v172, 0x12e80, v3
	v_add_u32_e32 v174, 0x13300, v3
	ds_read2_b32 v[88:89], v88 offset1:144
	ds_read_b32 v167, v90
	ds_read_b32 v177, v92
	ds_read_b32 v179, v94
	ds_read_b32 v181, v168
	ds_read_b32 v183, v170
	ds_read_b32 v185, v172
	ds_read_b32 v187, v174
	v_add_u32_e32 v90, 0x11a40, v3
	v_add_u32_e32 v92, 0x11ec0, v3
	v_add_u32_e32 v94, 0x12340, v3
	v_add_u32_e32 v168, 0x127c0, v3
	v_add_u32_e32 v170, 0x12c40, v3
	v_add_u32_e32 v172, 0x130c0, v3
	v_add_u32_e32 v174, 0x13540, v3
	ds_read_b32 v176, v90
	ds_read_b32 v178, v92
	ds_read_b32 v180, v94
	ds_read_b32 v182, v168
	ds_read_b32 v184, v170
	ds_read_b32 v186, v172
	ds_read_b32 v188, v174
	v_add_u32_e32 v90, 0x8c00, v3
	ds_read2_b32 v[90:91], v90 offset0:32 offset1:176
	v_add_u32_e32 v92, 0x9000, v3
	ds_read2_b32 v[92:93], v92 offset0:64 offset1:208
	v_add_u32_e32 v94, 0x9400, v3
	s_waitcnt lgkmcnt(14)
	v_fmac_f32_e32 v167, v166, v88
	ds_read2_b32 v[94:95], v94 offset0:96 offset1:240
	v_add_u32_e32 v168, 0x9a00, v3
	v_add_u32_e32 v170, 0x9e00, v3
	v_add_u32_e32 v172, 0xa200, v3
	v_add_u32_e32 v174, 0xa600, v3
	v_add_u32_e32 v189, 0x13780, v3
	v_add_u32_e32 v3, 0x139c0, v3
	s_waitcnt lgkmcnt(9)
	v_fmac_f32_e32 v176, v167, v89
	ds_read2_b32 v[168:169], v168 offset1:144
	ds_read2_b32 v[170:171], v170 offset0:32 offset1:176
	ds_read2_b32 v[172:173], v172 offset0:64 offset1:208
	ds_read2_b32 v[174:175], v174 offset0:96 offset1:240
	ds_read_b32 v189, v189
	ds_read_b32 v3, v3
	s_waitcnt lgkmcnt(8)
	v_fmac_f32_e32 v177, v176, v90
	v_cvt_pk_bf16_f32 v88, v167, v0
	v_add_u32_e32 v89, 0, v2
	v_fmac_f32_e32 v178, v177, v91
	ds_write_b16 v89, v88
	v_cvt_pk_bf16_f32 v88, v176, v0
	s_waitcnt lgkmcnt(8)
	v_fmac_f32_e32 v179, v178, v92
	ds_write_b16 v89, v88 offset:272
	v_cvt_pk_bf16_f32 v88, v177, v0
	v_fmac_f32_e32 v180, v179, v93
	ds_write_b16 v89, v88 offset:544
	v_cvt_pk_bf16_f32 v88, v178, v0
	s_waitcnt lgkmcnt(9)
	v_fmac_f32_e32 v181, v180, v94
	ds_write_b16 v89, v88 offset:816
	v_cvt_pk_bf16_f32 v88, v179, v0
	v_fmac_f32_e32 v182, v181, v95
	ds_write_b16 v89, v88 offset:1088
	v_cvt_pk_bf16_f32 v88, v180, v0
	s_waitcnt lgkmcnt(10)
	v_fmac_f32_e32 v183, v182, v168
	ds_write_b16 v89, v88 offset:1360
	v_cvt_pk_bf16_f32 v88, v181, v0
	v_fmac_f32_e32 v184, v183, v169
	ds_write_b16 v89, v88 offset:1632
	v_cvt_pk_bf16_f32 v88, v182, v0
	s_waitcnt lgkmcnt(11)
	v_fmac_f32_e32 v185, v184, v170
	ds_write_b16 v89, v88 offset:1904
	v_cvt_pk_bf16_f32 v88, v183, v0
	v_fmac_f32_e32 v186, v185, v171
	ds_write_b16 v89, v88 offset:2176
	v_cvt_pk_bf16_f32 v88, v184, v0
	s_waitcnt lgkmcnt(12)
	v_fmac_f32_e32 v187, v186, v172
	ds_write_b16 v89, v88 offset:2448
	v_cvt_pk_bf16_f32 v88, v185, v0
	v_fmac_f32_e32 v188, v187, v173
	ds_write_b16 v89, v88 offset:2720
	v_cvt_pk_bf16_f32 v88, v186, v0
	s_waitcnt lgkmcnt(12)
	v_fmac_f32_e32 v189, v188, v174
	ds_write_b16 v89, v88 offset:2992
	v_cvt_pk_bf16_f32 v88, v187, v0
	s_waitcnt lgkmcnt(12)
	v_fmac_f32_e32 v3, v189, v175
	ds_write_b16 v89, v88 offset:3264
	v_cvt_pk_bf16_f32 v88, v188, v0
	s_add_i32 s1, s1, 16
	ds_write_b16 v89, v88 offset:3536
	v_cvt_pk_bf16_f32 v88, v189, v0
	v_add_u32_e32 v2, 0x1100, v2
	v_add_u32_e32 v1, 0x2400, v1
	s_cmp_lt_u32 s1, 48
	v_mov_b32_e32 v166, v3
	ds_write_b16 v89, v88 offset:3808
	v_cvt_pk_bf16_f32 v88, v3, v0
	ds_write_b16 v89, v88 offset:4080
	s_cbranch_scc1 .LBB0_211
	s_setprio 0
	v_mov_b32_e32 v166, v3

; #define LAS __attribute__((address_space(3)))
; __device__ __forceinline__ float bf1(bf16_t h) { return __uint_as_float(((unsigned)h) << 16); }
; __device__ __forceinline__ float fast_sigmoid(float x) { return __builtin_amdgcn_rcpf(1.0f + __builtin_amdgcn_exp2f(-1.44269504089f * x)); }
; __device__ __forceinline__ void lru_item(const Args& a, int l, int item, LAS unsigned char* lds) {
;     ...
;         {
;             f32x4 accA[4], accX[4]; bf16x8 af[4][4]; bf16_t xr[4][4];
; #pragma unroll
;             for (int rb = 0; rb < 4; ++rb)
; #pragma unroll
;                 for (int ks = 0; ks < 4; ++ks) af[rb][ks] = *(const LAS bf16x8*)(At + (16 * rb + fr) * LRU_AS + (32 * ks + 8 * fq) * 2);
; #pragma unroll
;             for (int rb = 0; rb < 4; ++rb)
; #pragma unroll
;                 for (int j = 0; j < 4; ++j) xr[rb][j] = *(const LAS bf16_t*)(At + (16 * rb + 4 * fq + j) * LRU_AS + ecol * 2);
;             __builtin_amdgcn_sched_barrier(0);
; #pragma unroll
;             for (int rb = 0; rb < 4; ++rb) { accA[rb] = (f32x4){0.f, 0.f, 0.f, 0.f}; accX[rb] = (f32x4){0.f, 0.f, 0.f, 0.f}; }
; #pragma unroll
;             for (int ks = 0; ks < 4; ++ks)
; #pragma unroll
;                 for (int rb = 0; rb < 4; ++rb) {
;                     accA[rb] = __builtin_amdgcn_mfma_f32_16x16x32_bf16(af[rb][ks], wfa[ks], accA[rb], 0, 0, 0);
;                     accX[rb] = __builtin_amdgcn_mfma_f32_16x16x32_bf16(af[rb][ks], wfx[ks], accX[rb], 0, 0, 0);
;                 }
; #pragma unroll
;             for (int rb = 0; rb < 4; ++rb)
; #pragma unroll
;                 for (int j = 0; j < 4; ++j) {
;                     const int tt = 16 * rb + 4 * fq + j;
;                     const float xcv = bf1(xr[rb][j]);
;                     const float r = fast_sigmoid(accA[rb][j] + e_ba), ig = fast_sigmoid(accX[rb][j] + e_bx);
;                     const float la = e_coef * r;
;                     const float av = __builtin_amdgcn_exp2f(1.44269504089f * la);
;                     const float om = 1.0f - __builtin_amdgcn_exp2f(2.88539008178f * la);
;                     const float bv = __builtin_amdgcn_sqrtf(fmaxf(om, 0.f)) * ig * xcv;
;                     LA[tt * LRU_FS + ecol] = av; LB[tt * LRU_FS + ecol] = bv;
;                 }
.LBB0_255:
	ds_read_b128 v[88:91], v161
	ds_read_b128 v[92:95], v161 offset:64
	ds_read_b128 v[168:171], v161 offset:128
	ds_read_b128 v[172:175], v161 offset:192
	ds_read_b128 v[176:179], v161 offset:4352
	ds_read_b128 v[180:183], v161 offset:4416
	ds_read_b128 v[184:187], v161 offset:4480
	ds_read_b128 v[188:191], v161 offset:4544
	ds_read_b128 v[192:195], v161 offset:8704
	ds_read_b128 v[210:213], v161 offset:8768
	ds_read_b128 v[214:217], v161 offset:8832
	ds_read_b128 v[218:221], v161 offset:8896
	ds_read_b128 v[222:225], v161 offset:13056
	ds_read_b128 v[226:229], v161 offset:13120
	ds_read_b128 v[230:233], v161 offset:13184
	ds_read_b128 v[234:237], v161 offset:13248
	ds_read_u16 v3, v162
	ds_read_u16 v167, v163
	ds_read_u16 v196, v163 offset:272
	ds_read_u16 v197, v163 offset:544
	ds_read_u16 v209, v163 offset:4080
	ds_read_u16 v242, v163 offset:4352
	ds_read_u16 v243, v163 offset:4624
	ds_read_u16 v244, v163 offset:4896
	ds_read_u16 v245, v163 offset:8432
	ds_read_u16 v246, v163 offset:8704
	ds_read_u16 v247, v163 offset:8976
	ds_read_u16 v248, v163 offset:9248
	ds_read_u16 v249, v163 offset:12784
	ds_read_u16 v250, v163 offset:13056
	ds_read_u16 v2, v163 offset:13328
	ds_read_u16 v1, v163 offset:13600
	s_waitcnt lgkmcnt(14)
	v_mfma_f32_16x16x32_bf16 v[238:241], v[88:91], v[4:7], 0
	v_lshlrev_b32_e32 v3, 16, v3
	v_lshlrev_b32_e32 v167, 16, v167
	s_waitcnt lgkmcnt(1)
	v_lshlrev_b32_e32 v2, 16, v2
	v_mfma_f32_16x16x32_bf16 v[88:91], v[88:91], v[8:11], 0
	s_waitcnt lgkmcnt(0)
	v_lshlrev_b32_e32 v1, 16, v1
	v_mfma_f32_16x16x32_bf16 v[238:241], v[92:95], v[12:15], v[238:241]
	v_mfma_f32_16x16x32_bf16 v[88:91], v[92:95], v[16:19], v[88:91]
	v_mfma_f32_16x16x32_bf16 v[92:95], v[168:171], v[20:23], v[238:241]
	v_mfma_f32_16x16x32_bf16 v[92:95], v[172:175], v[28:31], v[92:95]
	v_mfma_f32_16x16x32_bf16 v[88:91], v[168:171], v[24:27], v[88:91]
	v_mfma_f32_16x16x32_bf16 v[88:91], v[172:175], v[32:35], v[88:91]
	s_nop 5
	v_add_f32_e32 v92, v122, v92
	v_mul_f32_e32 v92, 0xbfb8aa3b, v92
	v_exp_f32_e32 v92, v92
	v_add_f32_e32 v93, v122, v93
	v_mul_f32_e32 v93, 0xbfb8aa3b, v93
	v_add_f32_e32 v88, v123, v88
	v_add_f32_e32 v92, 1.0, v92
	v_rcp_f32_e32 v92, v92
	v_mul_f32_e32 v88, 0xbfb8aa3b, v88
	v_exp_f32_e32 v88, v88
	v_exp_f32_e32 v93, v93
	v_mul_f32_e32 v92, v100, v92
	v_mul_f32_e32 v168, 0x4038aa3b, v92
	v_exp_f32_e32 v168, v168
	v_add_f32_e32 v88, 1.0, v88
	v_rcp_f32_e32 v88, v88
	v_add_f32_e32 v93, 1.0, v93
	v_sub_f32_e32 v168, 1.0, v168
	v_max_f32_e32 v172, 0, v168
	v_sqrt_f32_e32 v238, v172
	v_rcp_f32_e32 v93, v93
	v_mul_f32_e32 v92, 0x3fb8aa3b, v92
	v_exp_f32_e32 v92, v92
	v_mul_f32_e32 v88, v88, v238
	v_mul_f32_e32 v3, v88, v3
	ds_write_b32 v120, v3
	v_mul_f32_e32 v3, v100, v93
	v_mul_f32_e32 v88, 0x4038aa3b, v3
	v_mul_f32_e32 v3, 0x3fb8aa3b, v3
	v_exp_f32_e32 v3, v3
	ds_write_b32 v103, v92 offset:34816
	v_add_f32_e32 v89, v123, v89
	v_mul_f32_e32 v89, 0xbfb8aa3b, v89
	ds_write_b32 v121, v3 offset:34816
	v_add_f32_e32 v3, v122, v94
	v_mul_f32_e32 v3, 0xbfb8aa3b, v3
	v_exp_f32_e32 v88, v88
	v_exp_f32_e32 v3, v3
	v_exp_f32_e32 v89, v89
	v_mfma_f32_16x16x32_bf16 v[168:171], v[176:179], v[4:7], 0
	v_sub_f32_e32 v88, 1.0, v88
	v_add_f32_e32 v3, 1.0, v3
	v_add_f32_e32 v89, 1.0, v89
	v_max_f32_e32 v88, 0, v88
	v_rcp_f32_e32 v3, v3
	v_rcp_f32_e32 v89, v89
	v_sqrt_f32_e32 v88, v88
	v_mfma_f32_16x16x32_bf16 v[172:175], v[176:179], v[8:11], 0
	v_mul_f32_e32 v3, v100, v3
	v_mul_f32_e32 v88, v89, v88
	v_add_f32_e32 v89, v123, v90
	v_mul_f32_e32 v90, 0x4038aa3b, v3
	v_mul_f32_e32 v3, 0x3fb8aa3b, v3
	v_exp_f32_e32 v3, v3
	v_mul_f32_e32 v88, v88, v167
	ds_write_b32 v124, v88
	v_mul_f32_e32 v89, 0xbfb8aa3b, v89
	v_exp_f32_e32 v90, v90
	ds_write_b32 v125, v3 offset:34816
	v_add_f32_e32 v3, v122, v95
	v_exp_f32_e32 v89, v89
	v_mul_f32_e32 v3, 0xbfb8aa3b, v3
	v_exp_f32_e32 v3, v3
	v_sub_f32_e32 v90, 1.0, v90
	v_add_f32_e32 v89, 1.0, v89
	v_max_f32_e32 v90, 0, v90
	v_rcp_f32_e32 v89, v89
	v_sqrt_f32_e32 v90, v90
	v_add_f32_e32 v3, 1.0, v3
	v_rcp_f32_e32 v3, v3
	v_mfma_f32_16x16x32_bf16 v[168:171], v[180:183], v[12:15], v[168:171]
	v_lshlrev_b32_e32 v88, 16, v196
	v_mul_f32_e32 v89, v89, v90
	v_mul_f32_e32 v88, v89, v88
	v_mfma_f32_16x16x32_bf16 v[172:175], v[180:183], v[16:19], v[172:175]
	v_mul_f32_e32 v3, v100, v3
	ds_write_b32 v126, v88
	v_add_f32_e32 v88, v123, v91
	v_mfma_f32_16x16x32_bf16 v[176:179], v[192:195], v[4:7], 0
	v_lshlrev_b32_e32 v167, 16, v197
	v_mfma_f32_16x16x32_bf16 v[192:195], v[192:195], v[8:11], 0
	v_mfma_f32_16x16x32_bf16 v[168:171], v[184:187], v[20:23], v[168:171]
	v_mfma_f32_16x16x32_bf16 v[172:175], v[184:187], v[24:27], v[172:175]
	v_mul_f32_e32 v185, 0x4038aa3b, v3
	v_mul_f32_e32 v184, 0xbfb8aa3b, v88
	v_exp_f32_e32 v185, v185
	v_exp_f32_e32 v184, v184
	v_mfma_f32_16x16x32_bf16 v[180:183], v[210:213], v[16:19], v[192:195]
	v_mul_f32_e32 v3, 0x3fb8aa3b, v3
	v_sub_f32_e32 v185, 1.0, v185
	v_add_f32_e32 v184, 1.0, v184
	v_max_f32_e32 v185, 0, v185
	v_mfma_f32_16x16x32_bf16 v[92:95], v[214:217], v[24:27], v[180:183]
	v_rcp_f32_e32 v184, v184
	v_sqrt_f32_e32 v185, v185
	v_exp_f32_e32 v3, v3
	v_mfma_f32_16x16x32_bf16 v[168:171], v[188:191], v[28:31], v[168:171]
	ds_write_b32 v127, v3 offset:34816
	v_mfma_f32_16x16x32_bf16 v[172:175], v[188:191], v[32:35], v[172:175]
	v_mul_f32_e32 v188, v184, v185
	s_nop 4
	v_add_f32_e32 v169, v122, v169
	v_mul_f32_e32 v169, 0xbfb8aa3b, v169
	v_mfma_f32_16x16x32_bf16 v[184:187], v[218:221], v[32:35], v[92:95]
	v_exp_f32_e32 v169, v169
	v_mul_f32_e32 v167, v188, v167
	ds_write_b32 v128, v167
	v_add_f32_e32 v92, v122, v168
	v_mul_f32_e32 v92, 0xbfb8aa3b, v92
	v_exp_f32_e32 v168, v92
; __device__ __forceinline__ float bf1(bf16_t h) { return __uint_as_float(((unsigned)h) << 16); }
; __device__ __forceinline__ float fast_sigmoid(float x) { return __builtin_amdgcn_rcpf(1.0f + __builtin_amdgcn_exp2f(-1.44269504089f * x)); }
; __device__ __forceinline__ void lru_item(const Args& a, int l, int item, LAS unsigned char* lds) {
;     ...
; #pragma unroll
;             for (int rb = 0; rb < 4; ++rb)
; #pragma unroll
;                 for (int j = 0; j < 4; ++j) {
;                     const int tt = 16 * rb + 4 * fq + j;
;                     const float xcv = bf1(xr[rb][j]);
;                     const float r = fast_sigmoid(accA[rb][j] + e_ba), ig = fast_sigmoid(accX[rb][j] + e_bx);
;                     const float la = e_coef * r;
;                     const float av = __builtin_amdgcn_exp2f(1.44269504089f * la);
;                     const float om = 1.0f - __builtin_amdgcn_exp2f(2.88539008178f * la);
;                     const float bv = __builtin_amdgcn_sqrtf(fmaxf(om, 0.f)) * ig * xcv;
;                     LA[tt * LRU_FS + ecol] = av; LB[tt * LRU_FS + ecol] = bv;
;                 }
	v_lshlrev_b32_e32 v167, 16, v209
	v_add_f32_e32 v170, v122, v170
	v_mul_f32_e32 v170, 0xbfb8aa3b, v170
	v_add_f32_e32 v3, 1.0, v168
	v_rcp_f32_e32 v3, v3
	v_add_f32_e32 v168, v123, v172
	v_mul_f32_e32 v168, 0xbfb8aa3b, v168
	v_exp_f32_e32 v168, v168
	v_mul_f32_e32 v3, v100, v3
	v_mul_f32_e32 v172, 0x4038aa3b, v3
	v_exp_f32_e32 v172, v172
	v_mul_f32_e32 v3, 0x3fb8aa3b, v3
	v_exp_f32_e32 v3, v3
	v_add_f32_e32 v168, 1.0, v168
	v_sub_f32_e32 v172, 1.0, v172
	v_max_f32_e32 v172, 0, v172
	ds_write_b32 v129, v3 offset:34816
	v_add_f32_e32 v3, 1.0, v169
	v_rcp_f32_e32 v168, v168
	v_sqrt_f32_e32 v172, v172
	v_rcp_f32_e32 v3, v3
	v_exp_f32_e32 v170, v170
	v_mfma_f32_16x16x32_bf16 v[176:179], v[210:213], v[12:15], v[176:179]
	v_mul_f32_e32 v168, v168, v172
	v_mul_f32_e32 v3, v100, v3
	v_mul_f32_e32 v167, v168, v167
	v_add_f32_e32 v168, v123, v173
	v_mul_f32_e32 v169, 0x4038aa3b, v3
	v_mul_f32_e32 v168, 0xbfb8aa3b, v168
	v_exp_f32_e32 v169, v169
	v_mul_f32_e32 v3, 0x3fb8aa3b, v3
	v_exp_f32_e32 v168, v168
	v_exp_f32_e32 v3, v3
	v_sub_f32_e32 v169, 1.0, v169
	ds_write_b32 v130, v167
	v_add_f32_e32 v168, 1.0, v168
	v_max_f32_e32 v169, 0, v169
	ds_write_b32 v131, v3 offset:34816
	v_add_f32_e32 v3, 1.0, v170
	v_rcp_f32_e32 v168, v168
	v_sqrt_f32_e32 v169, v169
	v_rcp_f32_e32 v3, v3
	v_lshlrev_b32_e32 v167, 16, v242
	v_add_f32_e32 v170, v122, v171
	v_mul_f32_e32 v168, v168, v169
	v_mul_f32_e32 v3, v100, v3
	v_mul_f32_e32 v167, v168, v167
	v_add_f32_e32 v168, v123, v174
	v_mul_f32_e32 v169, 0x4038aa3b, v3
	v_mul_f32_e32 v168, 0xbfb8aa3b, v168
	v_exp_f32_e32 v169, v169
	v_mul_f32_e32 v3, 0x3fb8aa3b, v3
	v_mul_f32_e32 v170, 0xbfb8aa3b, v170
	v_exp_f32_e32 v168, v168
	v_exp_f32_e32 v3, v3
	v_exp_f32_e32 v170, v170
	v_mfma_f32_16x16x32_bf16 v[176:179], v[214:217], v[20:23], v[176:179]
	v_sub_f32_e32 v169, 1.0, v169
	ds_write_b32 v132, v167
	v_add_f32_e32 v168, 1.0, v168
	v_max_f32_e32 v169, 0, v169
	ds_write_b32 v133, v3 offset:34816
	v_add_f32_e32 v3, 1.0, v170
	v_rcp_f32_e32 v168, v168
	v_sqrt_f32_e32 v169, v169
	v_rcp_f32_e32 v3, v3
	v_mfma_f32_16x16x32_bf16 v[176:179], v[218:221], v[28:31], v[176:179]
	v_lshlrev_b32_e32 v167, 16, v243
	v_mul_f32_e32 v168, v168, v169
	v_mul_f32_e32 v3, v100, v3
	v_mul_f32_e32 v167, v168, v167
	v_add_f32_e32 v168, v123, v175
	v_mul_f32_e32 v169, 0x4038aa3b, v3
	s_nop 1
	v_add_f32_e32 v170, v122, v176
	v_mul_f32_e32 v168, 0xbfb8aa3b, v168
	v_exp_f32_e32 v169, v169
	v_mul_f32_e32 v3, 0x3fb8aa3b, v3
	v_mul_f32_e32 v170, 0xbfb8aa3b, v170
	v_exp_f32_e32 v168, v168
	v_exp_f32_e32 v3, v3
	v_exp_f32_e32 v170, v170
	v_sub_f32_e32 v169, 1.0, v169
	ds_write_b32 v134, v167
	v_add_f32_e32 v168, 1.0, v168
	v_max_f32_e32 v169, 0, v169
	ds_write_b32 v135, v3 offset:34816
	v_add_f32_e32 v3, 1.0, v170
	v_rcp_f32_e32 v168, v168
	v_sqrt_f32_e32 v169, v169
	v_rcp_f32_e32 v3, v3
	v_lshlrev_b32_e32 v167, 16, v244
	v_add_f32_e32 v170, v122, v177
	v_mul_f32_e32 v168, v168, v169
	v_mul_f32_e32 v3, v100, v3
	v_mul_f32_e32 v167, v168, v167
	v_add_f32_e32 v168, v123, v184
	v_mul_f32_e32 v169, 0x4038aa3b, v3
	v_mul_f32_e32 v168, 0xbfb8aa3b, v168
	v_exp_f32_e32 v169, v169
	v_mul_f32_e32 v3, 0x3fb8aa3b, v3
	v_mul_f32_e32 v170, 0xbfb8aa3b, v170
	v_exp_f32_e32 v168, v168
	v_exp_f32_e32 v3, v3
	v_exp_f32_e32 v170, v170
	v_sub_f32_e32 v169, 1.0, v169
	ds_write_b32 v136, v167
	v_add_f32_e32 v168, 1.0, v168
	v_max_f32_e32 v169, 0, v169
	ds_write_b32 v137, v3 offset:34816
	v_add_f32_e32 v3, 1.0, v170
	v_rcp_f32_e32 v168, v168
	v_sqrt_f32_e32 v169, v169
	v_rcp_f32_e32 v3, v3
	v_lshlrev_b32_e32 v167, 16, v245
	v_add_f32_e32 v170, v122, v178
	v_mul_f32_e32 v168, v168, v169
	v_mul_f32_e32 v3, v100, v3
	v_mul_f32_e32 v167, v168, v167
	v_add_f32_e32 v168, v123, v185
	v_mul_f32_e32 v169, 0x4038aa3b, v3
	v_mul_f32_e32 v168, 0xbfb8aa3b, v168
	v_exp_f32_e32 v169, v169
	v_mul_f32_e32 v3, 0x3fb8aa3b, v3
	v_mul_f32_e32 v170, 0xbfb8aa3b, v170
	v_exp_f32_e32 v168, v168
	v_exp_f32_e32 v3, v3
	v_exp_f32_e32 v170, v170
	v_sub_f32_e32 v169, 1.0, v169
	ds_write_b32 v138, v167
	v_add_f32_e32 v168, 1.0, v168
	v_max_f32_e32 v169, 0, v169
	ds_write_b32 v139, v3 offset:34816
	v_add_f32_e32 v3, 1.0, v170
	v_rcp_f32_e32 v168, v168
	v_sqrt_f32_e32 v169, v169
	v_rcp_f32_e32 v3, v3
	v_mfma_f32_16x16x32_bf16 v[238:241], v[222:225], v[4:7], 0
	v_lshlrev_b32_e32 v167, 16, v246
	v_mul_f32_e32 v168, v168, v169
	v_mul_f32_e32 v3, v100, v3
	v_mul_f32_e32 v167, v168, v167
	v_add_f32_e32 v168, v123, v186
; __device__ __forceinline__ float bf1(bf16_t h) { return __uint_as_float(((unsigned)h) << 16); }
; __device__ __forceinline__ float fast_sigmoid(float x) { return __builtin_amdgcn_rcpf(1.0f + __builtin_amdgcn_exp2f(-1.44269504089f * x)); }
; __device__ __forceinline__ void lds_barrier() { asm volatile("s_waitcnt lgkmcnt(0)" ::: "memory"); __builtin_amdgcn_s_barrier(); asm volatile("" ::: "memory"); }
; __device__ __forceinline__ void lru_item(const Args& a, int l, int item, LAS unsigned char* lds) {
;     ...
;             for (int rb = 0; rb < 4; ++rb)
; #pragma unroll
;                 for (int j = 0; j < 4; ++j) {
;                     const int tt = 16 * rb + 4 * fq + j;
;                     const float xcv = bf1(xr[rb][j]);
;                     const float r = fast_sigmoid(accA[rb][j] + e_ba), ig = fast_sigmoid(accX[rb][j] + e_bx);
;                     const float la = e_coef * r;
;                     const float av = __builtin_amdgcn_exp2f(1.44269504089f * la);
;                     const float om = 1.0f - __builtin_amdgcn_exp2f(2.88539008178f * la);
;                     const float bv = __builtin_amdgcn_sqrtf(fmaxf(om, 0.f)) * ig * xcv;
;                     LA[tt * LRU_FS + ecol] = av; LB[tt * LRU_FS + ecol] = bv;
;                 }
;         }
;         lds_barrier();
;         if (tid < 128) {
; #pragma unroll 1
;             for (int t0 = 0; t0 < 64; t0 += 16) {
	v_mul_f32_e32 v169, 0x4038aa3b, v3
	v_add_f32_e32 v170, v122, v179
	v_mfma_f32_16x16x32_bf16 v[192:195], v[226:229], v[12:15], v[238:241]
	v_mul_f32_e32 v168, 0xbfb8aa3b, v168
	v_exp_f32_e32 v169, v169
	v_mul_f32_e32 v3, 0x3fb8aa3b, v3
	v_mul_f32_e32 v170, 0xbfb8aa3b, v170
	v_exp_f32_e32 v168, v168
	v_exp_f32_e32 v3, v3
	v_exp_f32_e32 v170, v170
	v_mfma_f32_16x16x32_bf16 v[180:183], v[230:233], v[20:23], v[192:195]
	v_sub_f32_e32 v169, 1.0, v169
	ds_write_b32 v140, v167
	v_add_f32_e32 v168, 1.0, v168
	v_max_f32_e32 v169, 0, v169
	ds_write_b32 v141, v3 offset:34816
	v_add_f32_e32 v3, 1.0, v170
	v_rcp_f32_e32 v168, v168
	v_sqrt_f32_e32 v169, v169
	v_rcp_f32_e32 v3, v3
	v_mfma_f32_16x16x32_bf16 v[222:225], v[222:225], v[8:11], 0
	v_lshlrev_b32_e32 v167, 16, v247
	v_mul_f32_e32 v168, v168, v169
	v_mul_f32_e32 v3, v100, v3
	v_mfma_f32_16x16x32_bf16 v[92:95], v[234:237], v[28:31], v[180:183]
	v_mul_f32_e32 v167, v168, v167
	v_add_f32_e32 v168, v123, v187
	v_mul_f32_e32 v169, 0x4038aa3b, v3
	v_mfma_f32_16x16x32_bf16 v[210:213], v[226:229], v[16:19], v[222:225]
	v_mul_f32_e32 v168, 0xbfb8aa3b, v168
	v_exp_f32_e32 v169, v169
	s_nop 1
	v_add_f32_e32 v92, v122, v92
	v_exp_f32_e32 v168, v168
	v_mul_f32_e32 v3, 0x3fb8aa3b, v3
	v_mul_f32_e32 v92, 0xbfb8aa3b, v92
	v_exp_f32_e32 v3, v3
	v_exp_f32_e32 v92, v92
	v_mfma_f32_16x16x32_bf16 v[88:91], v[230:233], v[24:27], v[210:213]
	v_sub_f32_e32 v169, 1.0, v169
	v_add_f32_e32 v168, 1.0, v168
	v_max_f32_e32 v169, 0, v169
	ds_write_b32 v142, v167
	v_rcp_f32_e32 v168, v168
	v_sqrt_f32_e32 v169, v169
	ds_write_b32 v143, v3 offset:34816
	v_add_f32_e32 v3, 1.0, v92
	v_rcp_f32_e32 v3, v3
	v_mfma_f32_16x16x32_bf16 v[88:91], v[234:237], v[32:35], v[88:91]
	v_lshlrev_b32_e32 v167, 16, v248
	v_mul_f32_e32 v168, v168, v169
	v_mul_f32_e32 v167, v168, v167
	v_mul_f32_e32 v3, v100, v3
	ds_write_b32 v144, v167
	s_nop 2
	v_add_f32_e32 v88, v123, v88
	v_mul_f32_e32 v167, 0x4038aa3b, v3
	v_add_f32_e32 v93, v122, v93
	v_mul_f32_e32 v88, 0xbfb8aa3b, v88
	v_exp_f32_e32 v167, v167
	v_mul_f32_e32 v3, 0x3fb8aa3b, v3
	v_mul_f32_e32 v93, 0xbfb8aa3b, v93
	v_exp_f32_e32 v88, v88
	v_exp_f32_e32 v3, v3
	v_exp_f32_e32 v93, v93
	v_sub_f32_e32 v167, 1.0, v167
	v_add_f32_e32 v88, 1.0, v88
	v_max_f32_e32 v167, 0, v167
	ds_write_b32 v145, v3 offset:34816
	v_add_f32_e32 v3, 1.0, v93
	v_rcp_f32_e32 v88, v88
	v_sqrt_f32_e32 v167, v167
	v_rcp_f32_e32 v3, v3
	v_lshlrev_b32_e32 v92, 16, v249
	v_add_f32_e32 v89, v123, v89
	v_mul_f32_e32 v88, v88, v167
	v_mul_f32_e32 v3, v100, v3
	v_mul_f32_e32 v88, v88, v92
	v_mul_f32_e32 v92, 0x4038aa3b, v3
	v_mul_f32_e32 v89, 0xbfb8aa3b, v89
	v_exp_f32_e32 v92, v92
	v_exp_f32_e32 v89, v89
	v_add_f32_e32 v93, v122, v94
	v_mul_f32_e32 v3, 0x3fb8aa3b, v3
	v_sub_f32_e32 v92, 1.0, v92
	v_add_f32_e32 v89, 1.0, v89
	v_max_f32_e32 v92, 0, v92
	v_rcp_f32_e32 v89, v89
	v_sqrt_f32_e32 v92, v92
	v_mul_f32_e32 v93, 0xbfb8aa3b, v93
	v_exp_f32_e32 v3, v3
	v_exp_f32_e32 v93, v93
	ds_write_b32 v146, v88
	v_lshlrev_b32_e32 v88, 16, v250
	v_mul_f32_e32 v89, v89, v92
	v_mul_f32_e32 v88, v89, v88
	ds_write_b32 v147, v3 offset:34816
	v_add_f32_e32 v3, 1.0, v93
	v_add_f32_e32 v89, v123, v90
	v_mul_f32_e32 v89, 0xbfb8aa3b, v89
	v_rcp_f32_e32 v3, v3
	v_exp_f32_e32 v89, v89
	ds_write_b32 v148, v88
	v_add_f32_e32 v90, v122, v95
	v_mul_f32_e32 v3, v100, v3
	v_add_f32_e32 v88, 1.0, v89
	v_mul_f32_e32 v89, 0x4038aa3b, v3
	v_exp_f32_e32 v89, v89
	v_mul_f32_e32 v3, 0x3fb8aa3b, v3
	v_mul_f32_e32 v90, 0xbfb8aa3b, v90
	v_exp_f32_e32 v3, v3
	v_exp_f32_e32 v90, v90
	v_sub_f32_e32 v89, 1.0, v89
	v_max_f32_e32 v89, 0, v89
	v_rcp_f32_e32 v88, v88
	v_sqrt_f32_e32 v89, v89
	ds_write_b32 v149, v3 offset:34816
	v_add_f32_e32 v3, 1.0, v90
	v_rcp_f32_e32 v3, v3
	v_mul_f32_e32 v88, v88, v89
	v_mul_f32_e32 v2, v88, v2
	v_add_f32_e32 v88, v123, v91
	v_mul_f32_e32 v3, v100, v3
	v_mul_f32_e32 v88, 0xbfb8aa3b, v88
	v_mul_f32_e32 v89, 0x4038aa3b, v3
	v_exp_f32_e32 v88, v88
	v_exp_f32_e32 v89, v89
	ds_write_b32 v150, v2
	v_mul_f32_e32 v3, 0x3fb8aa3b, v3
	v_add_f32_e32 v2, 1.0, v88
	v_sub_f32_e32 v88, 1.0, v89
	v_max_f32_e32 v88, 0, v88
	v_rcp_f32_e32 v2, v2
	v_sqrt_f32_e32 v88, v88
	v_exp_f32_e32 v3, v3
	v_mul_f32_e32 v2, v2, v88
	v_mul_f32_e32 v1, v2, v1
	ds_write_b32 v151, v3 offset:34816
	ds_write_b32 v152, v1
	s_waitcnt lgkmcnt(0)
	s_barrier
	s_and_saveexec_b64 s[12:13], s[42:43]
	s_cbranch_execz .LBB0_259
	s_mov_b32 s1, -16
	v_mov_b32_e32 v1, v160
	v_mov_b32_e32 v2, v153
	s_setprio 1

; #define LAS __attribute__((address_space(3)))
; __device__ __forceinline__ float bf1(bf16_t h) { return __uint_as_float(((unsigned)h) << 16); }
; __device__ __forceinline__ float fast_sigmoid(float x) { return __builtin_amdgcn_rcpf(1.0f + __builtin_amdgcn_exp2f(-1.44269504089f * x)); }
; __device__ __forceinline__ void lru_item(const Args& a, int l, int item, LAS unsigned char* lds) {
;     ...
;         {
;             f32x4 accA[4], accX[4]; bf16x8 af[4][4]; bf16_t xr[4][4];
; #pragma unroll
;             for (int rb = 0; rb < 4; ++rb)
; #pragma unroll
;                 for (int ks = 0; ks < 4; ++ks) af[rb][ks] = *(const LAS bf16x8*)(At + (16 * rb + fr) * LRU_AS + (32 * ks + 8 * fq) * 2);
; #pragma unroll
;             for (int rb = 0; rb < 4; ++rb)
; #pragma unroll
;                 for (int j = 0; j < 4; ++j) xr[rb][j] = *(const LAS bf16_t*)(At + (16 * rb + 4 * fq + j) * LRU_AS + ecol * 2);
;             __builtin_amdgcn_sched_barrier(0);
; #pragma unroll
;             for (int rb = 0; rb < 4; ++rb) { accA[rb] = (f32x4){0.f, 0.f, 0.f, 0.f}; accX[rb] = (f32x4){0.f, 0.f, 0.f, 0.f}; }
; #pragma unroll
;             for (int ks = 0; ks < 4; ++ks)
; #pragma unroll
;                 for (int rb = 0; rb < 4; ++rb) {
;                     accA[rb] = __builtin_amdgcn_mfma_f32_16x16x32_bf16(af[rb][ks], wfa[ks], accA[rb], 0, 0, 0);
;                     accX[rb] = __builtin_amdgcn_mfma_f32_16x16x32_bf16(af[rb][ks], wfx[ks], accX[rb], 0, 0, 0);
;                 }
; #pragma unroll
;             for (int rb = 0; rb < 4; ++rb)
; #pragma unroll
;                 for (int j = 0; j < 4; ++j) {
;                     const int tt = 16 * rb + 4 * fq + j;
;                     const float xcv = bf1(xr[rb][j]);
;                     const float r = fast_sigmoid(accA[rb][j] + e_ba), ig = fast_sigmoid(accX[rb][j] + e_bx);
;                     const float la = e_coef * r;
;                     const float av = __builtin_amdgcn_exp2f(1.44269504089f * la);
;                     const float om = 1.0f - __builtin_amdgcn_exp2f(2.88539008178f * la);
;                     const float bv = __builtin_amdgcn_sqrtf(fmaxf(om, 0.f)) * ig * xcv;
;                     LA[tt * LRU_FS + ecol] = av; LB[tt * LRU_FS + ecol] = bv;
;                 }
.LBB0_291:
	ds_read_b128 v[88:91], v161
	ds_read_b128 v[92:95], v161 offset:64
	ds_read_b128 v[168:171], v161 offset:128
	ds_read_b128 v[172:175], v161 offset:192
	ds_read_b128 v[176:179], v161 offset:4352
	ds_read_b128 v[180:183], v161 offset:4416
	ds_read_b128 v[184:187], v161 offset:4480
	ds_read_b128 v[188:191], v161 offset:4544
	ds_read_b128 v[192:195], v161 offset:8704
	ds_read_b128 v[210:213], v161 offset:8768
	ds_read_b128 v[214:217], v161 offset:8832
	ds_read_b128 v[218:221], v161 offset:8896
	ds_read_b128 v[222:225], v161 offset:13056
	ds_read_b128 v[226:229], v161 offset:13120
	ds_read_b128 v[230:233], v161 offset:13184
	ds_read_b128 v[234:237], v161 offset:13248
	ds_read_u16 v3, v162
	ds_read_u16 v167, v163
	ds_read_u16 v196, v163 offset:272
	ds_read_u16 v197, v163 offset:544
	ds_read_u16 v209, v163 offset:4080
	ds_read_u16 v242, v163 offset:4352
	ds_read_u16 v243, v163 offset:4624
	ds_read_u16 v244, v163 offset:4896
	ds_read_u16 v245, v163 offset:8432
	ds_read_u16 v246, v163 offset:8704
	ds_read_u16 v247, v163 offset:8976
	ds_read_u16 v248, v163 offset:9248
	ds_read_u16 v249, v163 offset:12784
	ds_read_u16 v250, v163 offset:13056
	ds_read_u16 v2, v163 offset:13328
	ds_read_u16 v1, v163 offset:13600
	s_waitcnt lgkmcnt(14)
	v_mfma_f32_16x16x32_bf16 v[238:241], v[88:91], v[4:7], 0
	v_lshlrev_b32_e32 v3, 16, v3
	v_lshlrev_b32_e32 v167, 16, v167
	s_waitcnt lgkmcnt(1)
	v_lshlrev_b32_e32 v2, 16, v2
	v_mfma_f32_16x16x32_bf16 v[88:91], v[88:91], v[8:11], 0
	s_waitcnt lgkmcnt(0)
	v_lshlrev_b32_e32 v1, 16, v1
	v_mfma_f32_16x16x32_bf16 v[238:241], v[92:95], v[12:15], v[238:241]
	v_mfma_f32_16x16x32_bf16 v[88:91], v[92:95], v[16:19], v[88:91]
	v_mfma_f32_16x16x32_bf16 v[92:95], v[168:171], v[20:23], v[238:241]
	v_mfma_f32_16x16x32_bf16 v[92:95], v[172:175], v[28:31], v[92:95]
	v_mfma_f32_16x16x32_bf16 v[88:91], v[168:171], v[24:27], v[88:91]
	v_mfma_f32_16x16x32_bf16 v[88:91], v[172:175], v[32:35], v[88:91]
	s_nop 5
	v_add_f32_e32 v92, v122, v92
	v_mul_f32_e32 v92, 0xbfb8aa3b, v92
	v_exp_f32_e32 v92, v92
	v_add_f32_e32 v93, v122, v93
	v_mul_f32_e32 v93, 0xbfb8aa3b, v93
	v_add_f32_e32 v88, v123, v88
	v_add_f32_e32 v92, 1.0, v92
	v_rcp_f32_e32 v92, v92
	v_mul_f32_e32 v88, 0xbfb8aa3b, v88
	v_exp_f32_e32 v88, v88
	v_exp_f32_e32 v93, v93
	v_mul_f32_e32 v92, v100, v92
	v_mul_f32_e32 v168, 0x4038aa3b, v92
	v_exp_f32_e32 v168, v168
	v_add_f32_e32 v88, 1.0, v88
	v_rcp_f32_e32 v88, v88
	v_add_f32_e32 v93, 1.0, v93
	v_sub_f32_e32 v168, 1.0, v168
	v_max_f32_e32 v172, 0, v168
	v_sqrt_f32_e32 v238, v172
	v_rcp_f32_e32 v93, v93
	v_mul_f32_e32 v92, 0x3fb8aa3b, v92
	v_exp_f32_e32 v92, v92
	v_mul_f32_e32 v88, v88, v238
	v_mul_f32_e32 v3, v88, v3
	ds_write_b32 v120, v3
	v_mul_f32_e32 v3, v100, v93
	v_mul_f32_e32 v88, 0x4038aa3b, v3
	v_mul_f32_e32 v3, 0x3fb8aa3b, v3
	v_exp_f32_e32 v3, v3
	ds_write_b32 v103, v92 offset:34816
	v_add_f32_e32 v89, v123, v89
	v_mul_f32_e32 v89, 0xbfb8aa3b, v89
	ds_write_b32 v121, v3 offset:34816
	v_add_f32_e32 v3, v122, v94
	v_mul_f32_e32 v3, 0xbfb8aa3b, v3
	v_exp_f32_e32 v88, v88
	v_exp_f32_e32 v3, v3
	v_exp_f32_e32 v89, v89
	v_mfma_f32_16x16x32_bf16 v[168:171], v[176:179], v[4:7], 0
	v_sub_f32_e32 v88, 1.0, v88
	v_add_f32_e32 v3, 1.0, v3
	v_add_f32_e32 v89, 1.0, v89
	v_max_f32_e32 v88, 0, v88
	v_rcp_f32_e32 v3, v3
	v_rcp_f32_e32 v89, v89
	v_sqrt_f32_e32 v88, v88
	v_mfma_f32_16x16x32_bf16 v[172:175], v[176:179], v[8:11], 0
	v_mul_f32_e32 v3, v100, v3
	v_mul_f32_e32 v88, v89, v88
	v_add_f32_e32 v89, v123, v90
	v_mul_f32_e32 v90, 0x4038aa3b, v3
	v_mul_f32_e32 v3, 0x3fb8aa3b, v3
	v_exp_f32_e32 v3, v3
	v_mul_f32_e32 v88, v88, v167
	ds_write_b32 v124, v88
	v_mul_f32_e32 v89, 0xbfb8aa3b, v89
	v_exp_f32_e32 v90, v90
	ds_write_b32 v125, v3 offset:34816
	v_add_f32_e32 v3, v122, v95
	v_exp_f32_e32 v89, v89
	v_mul_f32_e32 v3, 0xbfb8aa3b, v3
	v_exp_f32_e32 v3, v3
	v_sub_f32_e32 v90, 1.0, v90
	v_add_f32_e32 v89, 1.0, v89
	v_max_f32_e32 v90, 0, v90
	v_rcp_f32_e32 v89, v89
	v_sqrt_f32_e32 v90, v90
	v_add_f32_e32 v3, 1.0, v3
	v_rcp_f32_e32 v3, v3
	v_mfma_f32_16x16x32_bf16 v[168:171], v[180:183], v[12:15], v[168:171]
	v_lshlrev_b32_e32 v88, 16, v196
	v_mul_f32_e32 v89, v89, v90
	v_mul_f32_e32 v88, v89, v88
	v_mfma_f32_16x16x32_bf16 v[172:175], v[180:183], v[16:19], v[172:175]
	v_mul_f32_e32 v3, v100, v3
	ds_write_b32 v126, v88
	v_add_f32_e32 v88, v123, v91
	v_mfma_f32_16x16x32_bf16 v[176:179], v[192:195], v[4:7], 0
	v_lshlrev_b32_e32 v167, 16, v197
	v_mfma_f32_16x16x32_bf16 v[192:195], v[192:195], v[8:11], 0
	v_mfma_f32_16x16x32_bf16 v[168:171], v[184:187], v[20:23], v[168:171]
	v_mfma_f32_16x16x32_bf16 v[172:175], v[184:187], v[24:27], v[172:175]
	v_mul_f32_e32 v185, 0x4038aa3b, v3
	v_mul_f32_e32 v184, 0xbfb8aa3b, v88
	v_exp_f32_e32 v185, v185
	v_exp_f32_e32 v184, v184
	v_mfma_f32_16x16x32_bf16 v[180:183], v[210:213], v[16:19], v[192:195]
	v_mul_f32_e32 v3, 0x3fb8aa3b, v3
	v_sub_f32_e32 v185, 1.0, v185
	v_add_f32_e32 v184, 1.0, v184
	v_max_f32_e32 v185, 0, v185
	v_mfma_f32_16x16x32_bf16 v[92:95], v[214:217], v[24:27], v[180:183]
	v_rcp_f32_e32 v184, v184
	v_sqrt_f32_e32 v185, v185
	v_exp_f32_e32 v3, v3
	v_mfma_f32_16x16x32_bf16 v[168:171], v[188:191], v[28:31], v[168:171]
	ds_write_b32 v127, v3 offset:34816
	v_mfma_f32_16x16x32_bf16 v[172:175], v[188:191], v[32:35], v[172:175]
	v_mul_f32_e32 v188, v184, v185
	s_nop 4
	v_add_f32_e32 v169, v122, v169
	v_mul_f32_e32 v169, 0xbfb8aa3b, v169
	v_mfma_f32_16x16x32_bf16 v[184:187], v[218:221], v[32:35], v[92:95]
	v_exp_f32_e32 v169, v169
	v_mul_f32_e32 v167, v188, v167
	ds_write_b32 v128, v167
	v_add_f32_e32 v92, v122, v168
	v_mul_f32_e32 v92, 0xbfb8aa3b, v92
	v_exp_f32_e32 v168, v92
; __device__ __forceinline__ float bf1(bf16_t h) { return __uint_as_float(((unsigned)h) << 16); }
; __device__ __forceinline__ float fast_sigmoid(float x) { return __builtin_amdgcn_rcpf(1.0f + __builtin_amdgcn_exp2f(-1.44269504089f * x)); }
; __device__ __forceinline__ void lru_item(const Args& a, int l, int item, LAS unsigned char* lds) {
;     ...
; #pragma unroll
;             for (int rb = 0; rb < 4; ++rb)
; #pragma unroll
;                 for (int j = 0; j < 4; ++j) {
;                     const int tt = 16 * rb + 4 * fq + j;
;                     const float xcv = bf1(xr[rb][j]);
;                     const float r = fast_sigmoid(accA[rb][j] + e_ba), ig = fast_sigmoid(accX[rb][j] + e_bx);
;                     const float la = e_coef * r;
;                     const float av = __builtin_amdgcn_exp2f(1.44269504089f * la);
;                     const float om = 1.0f - __builtin_amdgcn_exp2f(2.88539008178f * la);
;                     const float bv = __builtin_amdgcn_sqrtf(fmaxf(om, 0.f)) * ig * xcv;
;                     LA[tt * LRU_FS + ecol] = av; LB[tt * LRU_FS + ecol] = bv;
;                 }
	v_lshlrev_b32_e32 v167, 16, v209
	v_add_f32_e32 v170, v122, v170
	v_mul_f32_e32 v170, 0xbfb8aa3b, v170
	v_add_f32_e32 v3, 1.0, v168
	v_rcp_f32_e32 v3, v3
	v_add_f32_e32 v168, v123, v172
	v_mul_f32_e32 v168, 0xbfb8aa3b, v168
	v_exp_f32_e32 v168, v168
	v_mul_f32_e32 v3, v100, v3
	v_mul_f32_e32 v172, 0x4038aa3b, v3
	v_exp_f32_e32 v172, v172
	v_mul_f32_e32 v3, 0x3fb8aa3b, v3
	v_exp_f32_e32 v3, v3
	v_add_f32_e32 v168, 1.0, v168
	v_sub_f32_e32 v172, 1.0, v172
	v_max_f32_e32 v172, 0, v172
	ds_write_b32 v129, v3 offset:34816
	v_add_f32_e32 v3, 1.0, v169
	v_rcp_f32_e32 v168, v168
	v_sqrt_f32_e32 v172, v172
	v_rcp_f32_e32 v3, v3
	v_exp_f32_e32 v170, v170
	v_mfma_f32_16x16x32_bf16 v[176:179], v[210:213], v[12:15], v[176:179]
	v_mul_f32_e32 v168, v168, v172
	v_mul_f32_e32 v3, v100, v3
	v_mul_f32_e32 v167, v168, v167
	v_add_f32_e32 v168, v123, v173
	v_mul_f32_e32 v169, 0x4038aa3b, v3
	v_mul_f32_e32 v168, 0xbfb8aa3b, v168
	v_exp_f32_e32 v169, v169
	v_mul_f32_e32 v3, 0x3fb8aa3b, v3
	v_exp_f32_e32 v168, v168
	v_exp_f32_e32 v3, v3
	v_sub_f32_e32 v169, 1.0, v169
	ds_write_b32 v130, v167
	v_add_f32_e32 v168, 1.0, v168
	v_max_f32_e32 v169, 0, v169
	ds_write_b32 v131, v3 offset:34816
	v_add_f32_e32 v3, 1.0, v170
	v_rcp_f32_e32 v168, v168
	v_sqrt_f32_e32 v169, v169
	v_rcp_f32_e32 v3, v3
	v_lshlrev_b32_e32 v167, 16, v242
	v_add_f32_e32 v170, v122, v171
	v_mul_f32_e32 v168, v168, v169
	v_mul_f32_e32 v3, v100, v3
	v_mul_f32_e32 v167, v168, v167
	v_add_f32_e32 v168, v123, v174
	v_mul_f32_e32 v169, 0x4038aa3b, v3
	v_mul_f32_e32 v168, 0xbfb8aa3b, v168
	v_exp_f32_e32 v169, v169
	v_mul_f32_e32 v3, 0x3fb8aa3b, v3
	v_mul_f32_e32 v170, 0xbfb8aa3b, v170
	v_exp_f32_e32 v168, v168
	v_exp_f32_e32 v3, v3
	v_exp_f32_e32 v170, v170
	v_mfma_f32_16x16x32_bf16 v[176:179], v[214:217], v[20:23], v[176:179]
	v_sub_f32_e32 v169, 1.0, v169
	ds_write_b32 v132, v167
	v_add_f32_e32 v168, 1.0, v168
	v_max_f32_e32 v169, 0, v169
	ds_write_b32 v133, v3 offset:34816
	v_add_f32_e32 v3, 1.0, v170
	v_rcp_f32_e32 v168, v168
	v_sqrt_f32_e32 v169, v169
	v_rcp_f32_e32 v3, v3
	v_mfma_f32_16x16x32_bf16 v[176:179], v[218:221], v[28:31], v[176:179]
	v_lshlrev_b32_e32 v167, 16, v243
	v_mul_f32_e32 v168, v168, v169
	v_mul_f32_e32 v3, v100, v3
	v_mul_f32_e32 v167, v168, v167
	v_add_f32_e32 v168, v123, v175
	v_mul_f32_e32 v169, 0x4038aa3b, v3
	s_nop 1
	v_add_f32_e32 v170, v122, v176
	v_mul_f32_e32 v168, 0xbfb8aa3b, v168
	v_exp_f32_e32 v169, v169
	v_mul_f32_e32 v3, 0x3fb8aa3b, v3
	v_mul_f32_e32 v170, 0xbfb8aa3b, v170
	v_exp_f32_e32 v168, v168
	v_exp_f32_e32 v3, v3
	v_exp_f32_e32 v170, v170
	v_sub_f32_e32 v169, 1.0, v169
	ds_write_b32 v134, v167
	v_add_f32_e32 v168, 1.0, v168
	v_max_f32_e32 v169, 0, v169
	ds_write_b32 v135, v3 offset:34816
	v_add_f32_e32 v3, 1.0, v170
	v_rcp_f32_e32 v168, v168
	v_sqrt_f32_e32 v169, v169
	v_rcp_f32_e32 v3, v3
	v_lshlrev_b32_e32 v167, 16, v244
	v_add_f32_e32 v170, v122, v177
	v_mul_f32_e32 v168, v168, v169
	v_mul_f32_e32 v3, v100, v3
	v_mul_f32_e32 v167, v168, v167
	v_add_f32_e32 v168, v123, v184
	v_mul_f32_e32 v169, 0x4038aa3b, v3
	v_mul_f32_e32 v168, 0xbfb8aa3b, v168
	v_exp_f32_e32 v169, v169
	v_mul_f32_e32 v3, 0x3fb8aa3b, v3
	v_mul_f32_e32 v170, 0xbfb8aa3b, v170
	v_exp_f32_e32 v168, v168
	v_exp_f32_e32 v3, v3
	v_exp_f32_e32 v170, v170
	v_sub_f32_e32 v169, 1.0, v169
	ds_write_b32 v136, v167
	v_add_f32_e32 v168, 1.0, v168
	v_max_f32_e32 v169, 0, v169
	ds_write_b32 v137, v3 offset:34816
	v_add_f32_e32 v3, 1.0, v170
	v_rcp_f32_e32 v168, v168
	v_sqrt_f32_e32 v169, v169
	v_rcp_f32_e32 v3, v3
	v_lshlrev_b32_e32 v167, 16, v245
	v_add_f32_e32 v170, v122, v178
	v_mul_f32_e32 v168, v168, v169
	v_mul_f32_e32 v3, v100, v3
	v_mul_f32_e32 v167, v168, v167
	v_add_f32_e32 v168, v123, v185
	v_mul_f32_e32 v169, 0x4038aa3b, v3
	v_mul_f32_e32 v168, 0xbfb8aa3b, v168
	v_exp_f32_e32 v169, v169
	v_mul_f32_e32 v3, 0x3fb8aa3b, v3
	v_mul_f32_e32 v170, 0xbfb8aa3b, v170
	v_exp_f32_e32 v168, v168
	v_exp_f32_e32 v3, v3
	v_exp_f32_e32 v170, v170
	v_sub_f32_e32 v169, 1.0, v169
	ds_write_b32 v138, v167
	v_add_f32_e32 v168, 1.0, v168
	v_max_f32_e32 v169, 0, v169
	ds_write_b32 v139, v3 offset:34816
	v_add_f32_e32 v3, 1.0, v170
	v_rcp_f32_e32 v168, v168
	v_sqrt_f32_e32 v169, v169
	v_rcp_f32_e32 v3, v3
	v_mfma_f32_16x16x32_bf16 v[238:241], v[222:225], v[4:7], 0
	v_lshlrev_b32_e32 v167, 16, v246
	v_mul_f32_e32 v168, v168, v169
	v_mul_f32_e32 v3, v100, v3
	v_mul_f32_e32 v167, v168, v167
	v_add_f32_e32 v168, v123, v186
	v_mul_f32_e32 v169, 0x4038aa3b, v3
	v_add_f32_e32 v170, v122, v179
	v_mfma_f32_16x16x32_bf16 v[192:195], v[226:229], v[12:15], v[238:241]
	v_mul_f32_e32 v168, 0xbfb8aa3b, v168
	v_exp_f32_e32 v169, v169
	v_mul_f32_e32 v3, 0x3fb8aa3b, v3
	v_mul_f32_e32 v170, 0xbfb8aa3b, v170
	v_exp_f32_e32 v168, v168
	v_exp_f32_e32 v3, v3
	v_exp_f32_e32 v170, v170
	v_mfma_f32_16x16x32_bf16 v[180:183], v[230:233], v[20:23], v[192:195]
	v_sub_f32_e32 v169, 1.0, v169
	ds_write_b32 v140, v167
	v_add_f32_e32 v168, 1.0, v168
	v_max_f32_e32 v169, 0, v169
	ds_write_b32 v141, v3 offset:34816
	v_add_f32_e32 v3, 1.0, v170
	v_rcp_f32_e32 v168, v168
	v_sqrt_f32_e32 v169, v169
	v_rcp_f32_e32 v3, v3
	v_mfma_f32_16x16x32_bf16 v[222:225], v[222:225], v[8:11], 0
	v_lshlrev_b32_e32 v167, 16, v247
	v_mul_f32_e32 v168, v168, v169
	v_mul_f32_e32 v3, v100, v3
	v_mfma_f32_16x16x32_bf16 v[92:95], v[234:237], v[28:31], v[180:183]
	v_mul_f32_e32 v167, v168, v167
	v_add_f32_e32 v168, v123, v187
	v_mul_f32_e32 v169, 0x4038aa3b, v3
	v_mfma_f32_16x16x32_bf16 v[210:213], v[226:229], v[16:19], v[222:225]
	v_mul_f32_e32 v168, 0xbfb8aa3b, v168
	v_exp_f32_e32 v169, v169
	s_nop 1
	v_add_f32_e32 v92, v122, v92
	v_exp_f32_e32 v168, v168
; #define LAS __attribute__((address_space(3)))
; __device__ __forceinline__ unsigned cvt_pk_bf16(float lo, float hi) { unsigned r; asm volatile("v_cvt_pk_bf16_f32 %0, %1, %2" : "=v"(r) : "v"(lo), "v"(hi)); return r; }
; __device__ __forceinline__ float bf1(bf16_t h) { return __uint_as_float(((unsigned)h) << 16); }
; __device__ __forceinline__ float fast_sigmoid(float x) { return __builtin_amdgcn_rcpf(1.0f + __builtin_amdgcn_exp2f(-1.44269504089f * x)); }
; __device__ __forceinline__ void lds_barrier() { asm volatile("s_waitcnt lgkmcnt(0)" ::: "memory"); __builtin_amdgcn_s_barrier(); asm volatile("" ::: "memory"); }
; __device__ __forceinline__ void lru_item(const Args& a, int l, int item, LAS unsigned char* lds) {
;     ...
;             for (int rb = 0; rb < 4; ++rb)
; #pragma unroll
;                 for (int j = 0; j < 4; ++j) {
;                     const int tt = 16 * rb + 4 * fq + j;
;                     const float xcv = bf1(xr[rb][j]);
;                     const float r = fast_sigmoid(accA[rb][j] + e_ba), ig = fast_sigmoid(accX[rb][j] + e_bx);
;                     const float la = e_coef * r;
;                     const float av = __builtin_amdgcn_exp2f(1.44269504089f * la);
;                     const float om = 1.0f - __builtin_amdgcn_exp2f(2.88539008178f * la);
;                     const float bv = __builtin_amdgcn_sqrtf(fmaxf(om, 0.f)) * ig * xcv;
;                     LA[tt * LRU_FS + ecol] = av; LB[tt * LRU_FS + ecol] = bv;
;                 }
;         }
;         lds_barrier();
;         if (tid < 128) {
; #pragma unroll 1
;             for (int t0 = 0; t0 < 64; t0 += 16) {
;                 float av[16], bv[16];
; #pragma unroll
;                 for (int i = 0; i < 16; ++i) { av[i] = LA[(t0 + i) * LRU_FS + tid]; bv[i] = LB[(t0 + i) * LRU_FS + tid]; }
; #pragma unroll
;                 for (int i = 0; i < 16; ++i) { hstate = av[i] * hstate + bv[i]; av[i] = hstate; }
; #pragma unroll
;                 for (int i = 0; i < 16; ++i) *(LAS bf16_t*)(HO + (t0 + i) * LRU_AS + tid * 2) = (bf16_t)(cvt_pk_bf16(av[i], 0.f) & 0xffffu);
;             }
;         }
	v_mul_f32_e32 v3, 0x3fb8aa3b, v3
	v_mul_f32_e32 v92, 0xbfb8aa3b, v92
	v_exp_f32_e32 v3, v3
	v_exp_f32_e32 v92, v92
	v_mfma_f32_16x16x32_bf16 v[88:91], v[230:233], v[24:27], v[210:213]
	v_sub_f32_e32 v169, 1.0, v169
	v_add_f32_e32 v168, 1.0, v168
	v_max_f32_e32 v169, 0, v169
	ds_write_b32 v142, v167
	v_rcp_f32_e32 v168, v168
	v_sqrt_f32_e32 v169, v169
	ds_write_b32 v143, v3 offset:34816
	v_add_f32_e32 v3, 1.0, v92
	v_rcp_f32_e32 v3, v3
	v_mfma_f32_16x16x32_bf16 v[88:91], v[234:237], v[32:35], v[88:91]
	v_lshlrev_b32_e32 v167, 16, v248
	v_mul_f32_e32 v168, v168, v169
	v_mul_f32_e32 v167, v168, v167
	v_mul_f32_e32 v3, v100, v3
	ds_write_b32 v144, v167
	s_nop 2
	v_add_f32_e32 v88, v123, v88
	v_mul_f32_e32 v167, 0x4038aa3b, v3
	v_add_f32_e32 v93, v122, v93
	v_mul_f32_e32 v88, 0xbfb8aa3b, v88
	v_exp_f32_e32 v167, v167
	v_mul_f32_e32 v3, 0x3fb8aa3b, v3
	v_mul_f32_e32 v93, 0xbfb8aa3b, v93
	v_exp_f32_e32 v88, v88
	v_exp_f32_e32 v3, v3
	v_exp_f32_e32 v93, v93
	v_sub_f32_e32 v167, 1.0, v167
	v_add_f32_e32 v88, 1.0, v88
	v_max_f32_e32 v167, 0, v167
	ds_write_b32 v145, v3 offset:34816
	v_add_f32_e32 v3, 1.0, v93
	v_rcp_f32_e32 v88, v88
	v_sqrt_f32_e32 v167, v167
	v_rcp_f32_e32 v3, v3
	v_lshlrev_b32_e32 v92, 16, v249
	v_add_f32_e32 v89, v123, v89
	v_mul_f32_e32 v88, v88, v167
	v_mul_f32_e32 v3, v100, v3
	v_mul_f32_e32 v88, v88, v92
	v_mul_f32_e32 v92, 0x4038aa3b, v3
	v_mul_f32_e32 v89, 0xbfb8aa3b, v89
	v_exp_f32_e32 v92, v92
	v_exp_f32_e32 v89, v89
	v_add_f32_e32 v93, v122, v94
	v_mul_f32_e32 v3, 0x3fb8aa3b, v3
	v_sub_f32_e32 v92, 1.0, v92
	v_add_f32_e32 v89, 1.0, v89
	v_max_f32_e32 v92, 0, v92
	v_rcp_f32_e32 v89, v89
	v_sqrt_f32_e32 v92, v92
	v_mul_f32_e32 v93, 0xbfb8aa3b, v93
	v_exp_f32_e32 v3, v3
	v_exp_f32_e32 v93, v93
	ds_write_b32 v146, v88
	v_lshlrev_b32_e32 v88, 16, v250
	v_mul_f32_e32 v89, v89, v92
	v_mul_f32_e32 v88, v89, v88
	ds_write_b32 v147, v3 offset:34816
	v_add_f32_e32 v3, 1.0, v93
	v_add_f32_e32 v89, v123, v90
	v_mul_f32_e32 v89, 0xbfb8aa3b, v89
	v_rcp_f32_e32 v3, v3
	v_exp_f32_e32 v89, v89
	ds_write_b32 v148, v88
	v_add_f32_e32 v90, v122, v95
	v_mul_f32_e32 v3, v100, v3
	v_add_f32_e32 v88, 1.0, v89
	v_mul_f32_e32 v89, 0x4038aa3b, v3
	v_exp_f32_e32 v89, v89
	v_mul_f32_e32 v3, 0x3fb8aa3b, v3
	v_mul_f32_e32 v90, 0xbfb8aa3b, v90
	v_exp_f32_e32 v3, v3
	v_exp_f32_e32 v90, v90
	v_sub_f32_e32 v89, 1.0, v89
	v_max_f32_e32 v89, 0, v89
	v_rcp_f32_e32 v88, v88
	v_sqrt_f32_e32 v89, v89
	ds_write_b32 v149, v3 offset:34816
	v_add_f32_e32 v3, 1.0, v90
	v_rcp_f32_e32 v3, v3
	v_mul_f32_e32 v88, v88, v89
	v_mul_f32_e32 v2, v88, v2
	v_add_f32_e32 v88, v123, v91
	v_mul_f32_e32 v3, v100, v3
	v_mul_f32_e32 v88, 0xbfb8aa3b, v88
	v_mul_f32_e32 v89, 0x4038aa3b, v3
	v_exp_f32_e32 v88, v88
	v_exp_f32_e32 v89, v89
	ds_write_b32 v150, v2
	v_mul_f32_e32 v3, 0x3fb8aa3b, v3
	v_add_f32_e32 v2, 1.0, v88
	v_sub_f32_e32 v88, 1.0, v89
	v_max_f32_e32 v88, 0, v88
	v_rcp_f32_e32 v2, v2
	v_sqrt_f32_e32 v88, v88
	v_exp_f32_e32 v3, v3
	v_mul_f32_e32 v2, v2, v88
	v_mul_f32_e32 v1, v2, v1
	ds_write_b32 v151, v3 offset:34816
	ds_write_b32 v152, v1
	s_waitcnt lgkmcnt(0)
	s_barrier
	s_and_saveexec_b64 s[2:3], s[42:43]
	s_cbranch_execz .LBB0_295
	s_mov_b32 s0, -16
	v_mov_b32_e32 v1, v160
	v_mov_b32_e32 v2, v153
	s_setprio 1
.LBB0_293:
	v_add_u32_e32 v3, 0, v1
	v_add_u32_e32 v88, 0x8800, v3
	v_add_u32_e32 v90, 0x11800, v3
	v_add_u32_e32 v92, 0x11c80, v3
	v_add_u32_e32 v94, 0x12100, v3
	v_add_u32_e32 v168, 0x12580, v3
	v_add_u32_e32 v170, 0x12a00, v3
	v_add_u32_e32 v172, 0x12e80, v3
	v_add_u32_e32 v174, 0x13300, v3
	ds_read2_b32 v[88:89], v88 offset1:144
	ds_read_b32 v167, v90
	ds_read_b32 v177, v92
	ds_read_b32 v179, v94
	ds_read_b32 v181, v168
	ds_read_b32 v183, v170
	ds_read_b32 v185, v172
	ds_read_b32 v187, v174
	v_add_u32_e32 v90, 0x11a40, v3
	v_add_u32_e32 v92, 0x11ec0, v3
	v_add_u32_e32 v94, 0x12340, v3
	v_add_u32_e32 v168, 0x127c0, v3
	v_add_u32_e32 v170, 0x12c40, v3
	v_add_u32_e32 v172, 0x130c0, v3
	v_add_u32_e32 v174, 0x13540, v3
	ds_read_b32 v176, v90
	ds_read_b32 v178, v92
	ds_read_b32 v180, v94
	ds_read_b32 v182, v168
	ds_read_b32 v184, v170
	ds_read_b32 v186, v172
	ds_read_b32 v188, v174
	v_add_u32_e32 v90, 0x8c00, v3
	ds_read2_b32 v[90:91], v90 offset0:32 offset1:176
	v_add_u32_e32 v92, 0x9000, v3
	ds_read2_b32 v[92:93], v92 offset0:64 offset1:208
	v_add_u32_e32 v94, 0x9400, v3
	s_waitcnt lgkmcnt(14)
	v_fmac_f32_e32 v167, v166, v88
	ds_read2_b32 v[94:95], v94 offset0:96 offset1:240
	v_add_u32_e32 v168, 0x9a00, v3
	v_add_u32_e32 v170, 0x9e00, v3
	v_add_u32_e32 v172, 0xa200, v3
	v_add_u32_e32 v174, 0xa600, v3
	v_add_u32_e32 v189, 0x13780, v3
	v_add_u32_e32 v3, 0x139c0, v3
	s_waitcnt lgkmcnt(9)
	v_fmac_f32_e32 v176, v167, v89
	ds_read2_b32 v[168:169], v168 offset1:144
	ds_read2_b32 v[170:171], v170 offset0:32 offset1:176
	ds_read2_b32 v[172:173], v172 offset0:64 offset1:208
	ds_read2_b32 v[174:175], v174 offset0:96 offset1:240
	ds_read_b32 v189, v189
	ds_read_b32 v3, v3
	s_waitcnt lgkmcnt(8)
	v_fmac_f32_e32 v177, v176, v90
	v_cvt_pk_bf16_f32 v88, v167, v0
	v_add_u32_e32 v89, 0, v2
	v_fmac_f32_e32 v178, v177, v91
	ds_write_b16 v89, v88
	v_cvt_pk_bf16_f32 v88, v176, v0
	s_waitcnt lgkmcnt(8)
	v_fmac_f32_e32 v179, v178, v92
	ds_write_b16 v89, v88 offset:272
	v_cvt_pk_bf16_f32 v88, v177, v0
	v_fmac_f32_e32 v180, v179, v93
	ds_write_b16 v89, v88 offset:544
	v_cvt_pk_bf16_f32 v88, v178, v0
	s_waitcnt lgkmcnt(9)
	v_fmac_f32_e32 v181, v180, v94
	ds_write_b16 v89, v88 offset:816
	v_cvt_pk_bf16_f32 v88, v179, v0
	v_fmac_f32_e32 v182, v181, v95
	ds_write_b16 v89, v88 offset:1088
	v_cvt_pk_bf16_f32 v88, v180, v0
	s_waitcnt lgkmcnt(10)
	v_fmac_f32_e32 v183, v182, v168
	ds_write_b16 v89, v88 offset:1360
	v_cvt_pk_bf16_f32 v88, v181, v0
	v_fmac_f32_e32 v184, v183, v169
	ds_write_b16 v89, v88 offset:1632
	v_cvt_pk_bf16_f32 v88, v182, v0
	s_waitcnt lgkmcnt(11)
	v_fmac_f32_e32 v185, v184, v170
	ds_write_b16 v89, v88 offset:1904
	v_cvt_pk_bf16_f32 v88, v183, v0
	v_fmac_f32_e32 v186, v185, v171
	ds_write_b16 v89, v88 offset:2176
	v_cvt_pk_bf16_f32 v88, v184, v0
	s_waitcnt lgkmcnt(12)
	v_fmac_f32_e32 v187, v186, v172
	ds_write_b16 v89, v88 offset:2448
	v_cvt_pk_bf16_f32 v88, v185, v0
	v_fmac_f32_e32 v188, v187, v173
	ds_write_b16 v89, v88 offset:2720
	v_cvt_pk_bf16_f32 v88, v186, v0
	s_waitcnt lgkmcnt(12)
	v_fmac_f32_e32 v189, v188, v174
	ds_write_b16 v89, v88 offset:2992
	v_cvt_pk_bf16_f32 v88, v187, v0
	s_waitcnt lgkmcnt(12)
	v_fmac_f32_e32 v3, v189, v175
	ds_write_b16 v89, v88 offset:3264
	v_cvt_pk_bf16_f32 v88, v188, v0
	s_add_i32 s0, s0, 16
	ds_write_b16 v89, v88 offset:3536
	v_cvt_pk_bf16_f32 v88, v189, v0
	v_add_u32_e32 v2, 0x1100, v2
	v_add_u32_e32 v1, 0x2400, v1
	s_cmp_lt_u32 s0, 48
	v_mov_b32_e32 v166, v3
	ds_write_b16 v89, v88 offset:3808
	v_cvt_pk_bf16_f32 v88, v3, v0
	ds_write_b16 v89, v88 offset:4080
	s_cbranch_scc1 .LBB0_293
	s_setprio 0
	v_mov_b32_e32 v166, v3
